# code placement: GEMM epilogue code of all three GEMM phases shifted by 4 bytes, K-loops unchanged
# speedup vs baseline: 1.0041x; 1.0041x over previous
.LBB0_225:
	ds_read_b128 v[132:135], v142
	ds_read_b128 v[136:139], v142 offset:1024
	ds_read_b128 v[150:153], v142 offset:2048
	ds_read_b128 v[154:157], v142 offset:3072
	s_add_i32 s69, s8, s68
	s_add_i32 s70, s69, 0x80080
	s_mov_b32 m0, s7
	ds_read_b128 v[158:161], v143
	ds_read_b128 v[162:165], v143 offset:1024
	ds_read_b128 v[166:169], v144
	ds_read_b128 v[170:173], v144 offset:1024
	ds_read_b128 v[178:181], v145
	ds_read_b128 v[214:217], v145 offset:1024
	ds_read_b128 v[218:221], v146
	ds_read_b128 v[222:225], v146 offset:1024
	buffer_load_dwordx4 v140, s[48:51], s70 offen lds
	s_mov_b32 m0, s6
	s_nop 0
	buffer_load_dwordx4 v141, s[48:51], s70 offen lds
	s_waitcnt lgkmcnt(8)
	s_barrier
	s_waitcnt lgkmcnt(0)
	s_setprio 1
	s_waitcnt lgkmcnt(0)
	v_mfma_f32_16x16x32_bf16 v[126:129], v[132:135], v[158:161], v[126:129]
	v_mfma_f32_16x16x32_bf16 v[122:125], v[150:153], v[158:161], v[122:125]
	v_mfma_f32_16x16x32_bf16 v[118:121], v[132:135], v[166:169], v[118:121]
	v_mfma_f32_16x16x32_bf16 v[114:117], v[150:153], v[166:169], v[114:117]
	v_mfma_f32_16x16x32_bf16 v[110:113], v[132:135], v[178:181], v[110:113]
	v_mfma_f32_16x16x32_bf16 v[106:109], v[150:153], v[178:181], v[106:109]
	v_mfma_f32_16x16x32_bf16 v[102:105], v[132:135], v[218:221], v[102:105]
	v_mfma_f32_16x16x32_bf16 v[98:101], v[150:153], v[218:221], v[98:101]
	v_mfma_f32_16x16x32_bf16 v[126:129], v[136:139], v[162:165], v[126:129]
	v_mfma_f32_16x16x32_bf16 v[122:125], v[154:157], v[162:165], v[122:125]
	v_mfma_f32_16x16x32_bf16 v[118:121], v[136:139], v[170:173], v[118:121]
	v_mfma_f32_16x16x32_bf16 v[114:117], v[154:157], v[170:173], v[114:117]
	v_mfma_f32_16x16x32_bf16 v[110:113], v[136:139], v[214:217], v[110:113]
	v_mfma_f32_16x16x32_bf16 v[106:109], v[154:157], v[214:217], v[106:109]
	v_mfma_f32_16x16x32_bf16 v[102:105], v[136:139], v[222:225], v[102:105]
	v_mfma_f32_16x16x32_bf16 v[98:101], v[154:157], v[222:225], v[98:101]
	s_setprio 0
	s_barrier
	s_add_i32 s70, s9, s68
	s_add_i32 s71, s70, 0x100
	s_mov_b32 m0, s28
	ds_read_b128 v[226:229], v147
	ds_read_b128 v[230:233], v147 offset:1024
	ds_read_b128 v[234:237], v147 offset:2048
	ds_read_b128 v[238:241], v147 offset:3072
	buffer_load_dwordx4 v140, s[44:47], s71 offen lds
	s_mov_b32 m0, s29
	s_nop 0
	buffer_load_dwordx4 v141, s[44:47], s71 offen lds
	s_barrier
	s_waitcnt lgkmcnt(0)
	s_setprio 1
	s_waitcnt lgkmcnt(0)
	v_mfma_f32_16x16x32_bf16 v[94:97], v[226:229], v[158:161], v[94:97]
	v_mfma_f32_16x16x32_bf16 v[90:93], v[234:237], v[158:161], v[90:93]
	v_mfma_f32_16x16x32_bf16 v[86:89], v[226:229], v[166:169], v[86:89]
	v_mfma_f32_16x16x32_bf16 v[82:85], v[234:237], v[166:169], v[82:85]
	v_mfma_f32_16x16x32_bf16 v[78:81], v[226:229], v[178:181], v[78:81]
	v_mfma_f32_16x16x32_bf16 v[74:77], v[234:237], v[178:181], v[74:77]
	v_mfma_f32_16x16x32_bf16 v[70:73], v[226:229], v[218:221], v[70:73]
	v_mfma_f32_16x16x32_bf16 v[66:69], v[234:237], v[218:221], v[66:69]
	v_mfma_f32_16x16x32_bf16 v[94:97], v[230:233], v[162:165], v[94:97]
	v_mfma_f32_16x16x32_bf16 v[90:93], v[238:241], v[162:165], v[90:93]
	v_mfma_f32_16x16x32_bf16 v[86:89], v[230:233], v[170:173], v[86:89]
	v_mfma_f32_16x16x32_bf16 v[82:85], v[238:241], v[170:173], v[82:85]
	v_mfma_f32_16x16x32_bf16 v[78:81], v[230:233], v[214:217], v[78:81]
	v_mfma_f32_16x16x32_bf16 v[74:77], v[238:241], v[214:217], v[74:77]
	v_mfma_f32_16x16x32_bf16 v[70:73], v[230:233], v[222:225], v[70:73]
	v_mfma_f32_16x16x32_bf16 v[66:69], v[238:241], v[222:225], v[66:69]
	s_setprio 0
	s_add_i32 s71, s69, 0x100
	s_mov_b32 m0, s27
	s_barrier
	ds_read_b128 v[158:161], v143 offset:16384
	ds_read_b128 v[162:165], v143 offset:17408
	ds_read_b128 v[166:169], v144 offset:16384
	ds_read_b128 v[170:173], v144 offset:17408
	ds_read_b128 v[178:181], v145 offset:16384
	ds_read_b128 v[214:217], v145 offset:17408
	ds_read_b128 v[218:221], v146 offset:16384
	ds_read_b128 v[222:225], v146 offset:17408
	buffer_load_dwordx4 v140, s[48:51], s71 offen lds
	s_mov_b32 m0, s30
	s_nop 0
	buffer_load_dwordx4 v141, s[48:51], s71 offen lds
	s_barrier
	s_waitcnt lgkmcnt(0)
	s_setprio 1
	s_waitcnt lgkmcnt(0)
	v_mfma_f32_16x16x32_bf16 v[62:65], v[132:135], v[158:161], v[62:65]
	v_mfma_f32_16x16x32_bf16 v[58:61], v[150:153], v[158:161], v[58:61]
	v_mfma_f32_16x16x32_bf16 v[54:57], v[132:135], v[166:169], v[54:57]
	v_mfma_f32_16x16x32_bf16 v[50:53], v[150:153], v[166:169], v[50:53]
	v_mfma_f32_16x16x32_bf16 v[46:49], v[132:135], v[178:181], v[46:49]
	v_mfma_f32_16x16x32_bf16 v[42:45], v[150:153], v[178:181], v[42:45]
	v_mfma_f32_16x16x32_bf16 v[38:41], v[132:135], v[218:221], v[38:41]
	v_mfma_f32_16x16x32_bf16 v[34:37], v[150:153], v[218:221], v[34:37]
	v_mfma_f32_16x16x32_bf16 v[62:65], v[136:139], v[162:165], v[62:65]
	v_mfma_f32_16x16x32_bf16 v[58:61], v[154:157], v[162:165], v[58:61]
	v_mfma_f32_16x16x32_bf16 v[54:57], v[136:139], v[170:173], v[54:57]
	v_mfma_f32_16x16x32_bf16 v[50:53], v[154:157], v[170:173], v[50:53]
	v_mfma_f32_16x16x32_bf16 v[46:49], v[136:139], v[214:217], v[46:49]
	v_mfma_f32_16x16x32_bf16 v[42:45], v[154:157], v[214:217], v[42:45]
	v_mfma_f32_16x16x32_bf16 v[38:41], v[136:139], v[222:225], v[38:41]
	v_mfma_f32_16x16x32_bf16 v[34:37], v[154:157], v[222:225], v[34:37]
	s_setprio 0
	s_barrier
	s_add_i32 s71, s70, 0x80100
	s_mov_b32 m0, s31
	s_nop 0
	buffer_load_dwordx4 v140, s[44:47], s71 offen lds
	s_mov_b32 m0, s34
	s_nop 0
	buffer_load_dwordx4 v141, s[44:47], s71 offen lds
	s_waitcnt vmcnt(6)
	s_barrier
	s_setprio 1
	v_mfma_f32_16x16x32_bf16 v[30:33], v[226:229], v[158:161], v[30:33]
	v_mfma_f32_16x16x32_bf16 v[26:29], v[234:237], v[158:161], v[26:29]
	v_mfma_f32_16x16x32_bf16 v[22:25], v[226:229], v[166:169], v[22:25]
	v_mfma_f32_16x16x32_bf16 v[18:21], v[234:237], v[166:169], v[18:21]
	v_mfma_f32_16x16x32_bf16 v[12:15], v[226:229], v[178:181], v[12:15]
	v_mfma_f32_16x16x32_bf16 v[8:11], v[234:237], v[178:181], v[8:11]
	v_mfma_f32_16x16x32_bf16 v[4:7], v[226:229], v[218:221], v[4:7]
	v_mfma_f32_16x16x32_bf16 v[0:3], v[234:237], v[218:221], v[0:3]
	v_mfma_f32_16x16x32_bf16 v[30:33], v[230:233], v[162:165], v[30:33]
	v_mfma_f32_16x16x32_bf16 v[26:29], v[238:241], v[162:165], v[26:29]
	v_mfma_f32_16x16x32_bf16 v[22:25], v[230:233], v[170:173], v[22:25]
	v_mfma_f32_16x16x32_bf16 v[18:21], v[238:241], v[170:173], v[18:21]
	v_mfma_f32_16x16x32_bf16 v[12:15], v[230:233], v[214:217], v[12:15]
	v_mfma_f32_16x16x32_bf16 v[8:11], v[238:241], v[214:217], v[8:11]
	v_mfma_f32_16x16x32_bf16 v[4:7], v[230:233], v[222:225], v[4:7]
	v_mfma_f32_16x16x32_bf16 v[0:3], v[238:241], v[222:225], v[0:3]
	s_setprio 0
	s_barrier
	ds_read_b128 v[132:135], v148
	ds_read_b128 v[136:139], v148 offset:1024
	ds_read_b128 v[150:153], v148 offset:2048
	ds_read_b128 v[154:157], v148 offset:3072
	s_add_i32 s71, s69, 0x80100
	s_mov_b32 m0, s35
	ds_read_b128 v[158:161], v143 offset:32768
	ds_read_b128 v[162:165], v143 offset:33792
	ds_read_b128 v[166:169], v144 offset:32768
	ds_read_b128 v[170:173], v144 offset:33792
	ds_read_b128 v[178:181], v145 offset:32768
	ds_read_b128 v[214:217], v145 offset:33792
	ds_read_b128 v[218:221], v146 offset:32768
	ds_read_b128 v[222:225], v146 offset:33792
	buffer_load_dwordx4 v140, s[48:51], s71 offen lds
	s_mov_b32 m0, s36
	s_nop 0
	buffer_load_dwordx4 v141, s[48:51], s71 offen lds
	s_waitcnt lgkmcnt(8)
	s_barrier
	s_waitcnt lgkmcnt(0)
	s_setprio 1
	s_waitcnt lgkmcnt(0)
	v_mfma_f32_16x16x32_bf16 v[126:129], v[132:135], v[158:161], v[126:129]
	v_mfma_f32_16x16x32_bf16 v[122:125], v[150:153], v[158:161], v[122:125]
	v_mfma_f32_16x16x32_bf16 v[118:121], v[132:135], v[166:169], v[118:121]
	v_mfma_f32_16x16x32_bf16 v[114:117], v[150:153], v[166:169], v[114:117]
	v_mfma_f32_16x16x32_bf16 v[110:113], v[132:135], v[178:181], v[110:113]
	v_mfma_f32_16x16x32_bf16 v[106:109], v[150:153], v[178:181], v[106:109]
	v_mfma_f32_16x16x32_bf16 v[102:105], v[132:135], v[218:221], v[102:105]
	v_mfma_f32_16x16x32_bf16 v[98:101], v[150:153], v[218:221], v[98:101]
	v_mfma_f32_16x16x32_bf16 v[126:129], v[136:139], v[162:165], v[126:129]
	v_mfma_f32_16x16x32_bf16 v[122:125], v[154:157], v[162:165], v[122:125]
	v_mfma_f32_16x16x32_bf16 v[118:121], v[136:139], v[170:173], v[118:121]
	v_mfma_f32_16x16x32_bf16 v[114:117], v[154:157], v[170:173], v[114:117]
	v_mfma_f32_16x16x32_bf16 v[110:113], v[136:139], v[214:217], v[110:113]
	v_mfma_f32_16x16x32_bf16 v[106:109], v[154:157], v[214:217], v[106:109]
	v_mfma_f32_16x16x32_bf16 v[102:105], v[136:139], v[222:225], v[102:105]
	v_mfma_f32_16x16x32_bf16 v[98:101], v[154:157], v[222:225], v[98:101]
	s_setprio 0
	s_barrier
	s_add_i32 s71, s70, 0x180
	s_mov_b32 m0, s37
	ds_read_b128 v[226:229], v149
	ds_read_b128 v[230:233], v149 offset:1024
	ds_read_b128 v[234:237], v149 offset:2048
	ds_read_b128 v[238:241], v149 offset:3072
	buffer_load_dwordx4 v140, s[44:47], s71 offen lds
	s_mov_b32 m0, s38
	s_nop 0
	buffer_load_dwordx4 v141, s[44:47], s71 offen lds
	s_barrier
	s_waitcnt lgkmcnt(0)
	s_setprio 1
	s_waitcnt lgkmcnt(0)
	v_mfma_f32_16x16x32_bf16 v[94:97], v[226:229], v[158:161], v[94:97]
	v_mfma_f32_16x16x32_bf16 v[90:93], v[234:237], v[158:161], v[90:93]
	v_mfma_f32_16x16x32_bf16 v[86:89], v[226:229], v[166:169], v[86:89]
	v_mfma_f32_16x16x32_bf16 v[82:85], v[234:237], v[166:169], v[82:85]
	v_mfma_f32_16x16x32_bf16 v[78:81], v[226:229], v[178:181], v[78:81]
	v_mfma_f32_16x16x32_bf16 v[74:77], v[234:237], v[178:181], v[74:77]
	v_mfma_f32_16x16x32_bf16 v[70:73], v[226:229], v[218:221], v[70:73]
	v_mfma_f32_16x16x32_bf16 v[66:69], v[234:237], v[218:221], v[66:69]
	v_mfma_f32_16x16x32_bf16 v[94:97], v[230:233], v[162:165], v[94:97]
	v_mfma_f32_16x16x32_bf16 v[90:93], v[238:241], v[162:165], v[90:93]
	v_mfma_f32_16x16x32_bf16 v[86:89], v[230:233], v[170:173], v[86:89]
	v_mfma_f32_16x16x32_bf16 v[82:85], v[238:241], v[170:173], v[82:85]
	v_mfma_f32_16x16x32_bf16 v[78:81], v[230:233], v[214:217], v[78:81]
	v_mfma_f32_16x16x32_bf16 v[74:77], v[238:241], v[214:217], v[74:77]
	v_mfma_f32_16x16x32_bf16 v[70:73], v[230:233], v[222:225], v[70:73]
	v_mfma_f32_16x16x32_bf16 v[66:69], v[238:241], v[222:225], v[66:69]
	s_setprio 0
	s_addk_i32 s69, 0x180
	s_mov_b32 m0, s39
	s_barrier
	ds_read_b128 v[158:161], v143 offset:49152
	ds_read_b128 v[162:165], v143 offset:50176
	ds_read_b128 v[166:169], v144 offset:49152
	ds_read_b128 v[170:173], v144 offset:50176
	ds_read_b128 v[178:181], v145 offset:49152
	ds_read_b128 v[214:217], v145 offset:50176
	ds_read_b128 v[218:221], v146 offset:49152
	ds_read_b128 v[222:225], v146 offset:50176
	buffer_load_dwordx4 v140, s[48:51], s69 offen lds
	s_mov_b32 m0, s62
	s_nop 0
	buffer_load_dwordx4 v141, s[48:51], s69 offen lds
	s_barrier
	s_waitcnt lgkmcnt(0)
	s_setprio 1
	s_waitcnt lgkmcnt(0)
	v_mfma_f32_16x16x32_bf16 v[62:65], v[132:135], v[158:161], v[62:65]
	v_mfma_f32_16x16x32_bf16 v[58:61], v[150:153], v[158:161], v[58:61]
	v_mfma_f32_16x16x32_bf16 v[54:57], v[132:135], v[166:169], v[54:57]
	v_mfma_f32_16x16x32_bf16 v[50:53], v[150:153], v[166:169], v[50:53]
	v_mfma_f32_16x16x32_bf16 v[46:49], v[132:135], v[178:181], v[46:49]
	v_mfma_f32_16x16x32_bf16 v[42:45], v[150:153], v[178:181], v[42:45]
	v_mfma_f32_16x16x32_bf16 v[38:41], v[132:135], v[218:221], v[38:41]
	v_mfma_f32_16x16x32_bf16 v[34:37], v[150:153], v[218:221], v[34:37]
	v_mfma_f32_16x16x32_bf16 v[62:65], v[136:139], v[162:165], v[62:65]
	v_mfma_f32_16x16x32_bf16 v[58:61], v[154:157], v[162:165], v[58:61]
	v_mfma_f32_16x16x32_bf16 v[54:57], v[136:139], v[170:173], v[54:57]
	v_mfma_f32_16x16x32_bf16 v[50:53], v[154:157], v[170:173], v[50:53]
	v_mfma_f32_16x16x32_bf16 v[46:49], v[136:139], v[214:217], v[46:49]
	v_mfma_f32_16x16x32_bf16 v[42:45], v[154:157], v[214:217], v[42:45]
	v_mfma_f32_16x16x32_bf16 v[38:41], v[136:139], v[222:225], v[38:41]
	v_mfma_f32_16x16x32_bf16 v[34:37], v[154:157], v[222:225], v[34:37]
	s_setprio 0
	s_barrier
	s_add_i32 s70, s70, 0x80180
	s_mov_b32 m0, s63
	s_nop 0
	buffer_load_dwordx4 v140, s[44:47], s70 offen lds
	s_mov_b32 m0, s66
	s_nop 0
	buffer_load_dwordx4 v141, s[44:47], s70 offen lds
	s_waitcnt vmcnt(6)
	s_barrier
	s_setprio 1
	v_mfma_f32_16x16x32_bf16 v[30:33], v[226:229], v[158:161], v[30:33]
	v_mfma_f32_16x16x32_bf16 v[26:29], v[234:237], v[158:161], v[26:29]
	v_mfma_f32_16x16x32_bf16 v[22:25], v[226:229], v[166:169], v[22:25]
	v_mfma_f32_16x16x32_bf16 v[18:21], v[234:237], v[166:169], v[18:21]
	v_mfma_f32_16x16x32_bf16 v[12:15], v[226:229], v[178:181], v[12:15]
	v_mfma_f32_16x16x32_bf16 v[8:11], v[234:237], v[178:181], v[8:11]
	v_mfma_f32_16x16x32_bf16 v[4:7], v[226:229], v[218:221], v[4:7]
	v_mfma_f32_16x16x32_bf16 v[0:3], v[234:237], v[218:221], v[0:3]
	v_mfma_f32_16x16x32_bf16 v[30:33], v[230:233], v[162:165], v[30:33]
	v_mfma_f32_16x16x32_bf16 v[26:29], v[238:241], v[162:165], v[26:29]
	v_mfma_f32_16x16x32_bf16 v[22:25], v[230:233], v[170:173], v[22:25]
	v_mfma_f32_16x16x32_bf16 v[18:21], v[238:241], v[170:173], v[18:21]
	v_mfma_f32_16x16x32_bf16 v[12:15], v[230:233], v[214:217], v[12:15]
	v_mfma_f32_16x16x32_bf16 v[8:11], v[238:241], v[214:217], v[8:11]
	v_mfma_f32_16x16x32_bf16 v[4:7], v[230:233], v[222:225], v[4:7]
	v_mfma_f32_16x16x32_bf16 v[0:3], v[238:241], v[222:225], v[0:3]
	s_setprio 0
	s_add_i32 s67, s67, 2
	s_addk_i32 s68, 0x100
	s_cmp_lt_u32 s67, 28
	s_barrier
	s_cbranch_scc1 .LBB0_225
	v_mov_b32_e32 v150, v130
	s_or_b32 s8, s8, 0x80f80
	v_and_b32_e32 v158, 15, v150
	v_bfe_u32 v132, v150, 4, 2
	v_lshlrev_b32_e32 v134, 2, v150
	v_bfe_u32 v152, v150, 6, 2
	v_lshlrev_b32_e32 v151, 4, v132
	v_lshlrev_b32_e32 v133, 6, v158
	v_and_b32_e32 v139, 32, v134
	v_lshlrev_b32_e32 v138, 12, v152
	v_bitop3_b32 v153, v151, v139, v133 bitop3:0x36
	v_add3_u32 v133, s78, v153, v138
	ds_read_b128 v[134:137], v133
	ds_read_b128 v[154:157], v133 offset:1024
	ds_read_b128 v[160:163], v133 offset:2048
	ds_read_b128 v[164:167], v133 offset:3072
	v_ashrrev_i32_e32 v133, 2, v150
	v_lshlrev_b32_e32 v172, 6, v150
	v_and_b32_e32 v133, 0xffffffc0, v133
	v_and_b32_e32 v172, 0x3c0, v172
	v_lshlrev_b32_e32 v159, 7, v133
	v_bitop3_b32 v139, v172, v139, v151 bitop3:0x36
	s_waitcnt vmcnt(0)
	v_add3_u32 v176, 0, v153, v159
	v_add3_u32 v139, 0, v139, v159
	s_mov_b32 m0, s7
	ds_read_b128 v[168:171], v176
	ds_read_b128 v[178:181], v176 offset:1024
	ds_read_b128 v[214:217], v139 offset:2048
	ds_read_b128 v[218:221], v139 offset:3072
	ds_read_b128 v[222:225], v139 offset:4096
	ds_read_b128 v[226:229], v139 offset:5120
	ds_read_b128 v[230:233], v139 offset:6144
	ds_read_b128 v[234:237], v139 offset:7168
	buffer_load_dwordx4 v140, s[48:51], s8 offen lds
	s_mov_b32 m0, s6
	s_nop 0
	buffer_load_dwordx4 v141, s[48:51], s8 offen lds
	s_barrier
	s_waitcnt lgkmcnt(0)
	s_setprio 1
	s_waitcnt lgkmcnt(0)
	v_mfma_f32_16x16x32_bf16 v[126:129], v[134:137], v[168:171], v[126:129]
	v_mfma_f32_16x16x32_bf16 v[122:125], v[160:163], v[168:171], v[122:125]
	v_mfma_f32_16x16x32_bf16 v[118:121], v[134:137], v[214:217], v[118:121]
	v_mfma_f32_16x16x32_bf16 v[114:117], v[160:163], v[214:217], v[114:117]
	v_mfma_f32_16x16x32_bf16 v[110:113], v[134:137], v[222:225], v[110:113]
	v_mfma_f32_16x16x32_bf16 v[106:109], v[160:163], v[222:225], v[106:109]
	v_mfma_f32_16x16x32_bf16 v[102:105], v[134:137], v[230:233], v[102:105]
	v_mfma_f32_16x16x32_bf16 v[98:101], v[160:163], v[230:233], v[98:101]
	v_mfma_f32_16x16x32_bf16 v[126:129], v[154:157], v[178:181], v[126:129]
	v_mfma_f32_16x16x32_bf16 v[122:125], v[164:167], v[178:181], v[122:125]
	v_mfma_f32_16x16x32_bf16 v[118:121], v[154:157], v[218:221], v[118:121]
	v_mfma_f32_16x16x32_bf16 v[114:117], v[164:167], v[218:221], v[114:117]
	v_mfma_f32_16x16x32_bf16 v[110:113], v[154:157], v[226:229], v[110:113]
	v_mfma_f32_16x16x32_bf16 v[106:109], v[164:167], v[226:229], v[106:109]
	v_mfma_f32_16x16x32_bf16 v[102:105], v[154:157], v[234:237], v[102:105]
	v_mfma_f32_16x16x32_bf16 v[98:101], v[164:167], v[234:237], v[98:101]
	s_setprio 0
	v_add3_u32 v159, s77, v153, v138
	s_barrier
	ds_read_b128 v[238:241], v159
	ds_read_b128 v[242:245], v159 offset:1024
	ds_read_b128 v[246:249], v159 offset:2048
	ds_read_b128 v[250:253], v159 offset:3072
	s_barrier
	s_waitcnt lgkmcnt(0)
	s_setprio 1
	s_waitcnt lgkmcnt(0)
	v_mfma_f32_16x16x32_bf16 v[94:97], v[238:241], v[168:171], v[94:97]
	v_mfma_f32_16x16x32_bf16 v[182:185], v[242:245], v[178:181], v[94:97]
	v_mfma_f32_16x16x32_bf16 v[90:93], v[246:249], v[168:171], v[90:93]
	v_mfma_f32_16x16x32_bf16 v[86:89], v[238:241], v[214:217], v[86:89]
	v_mfma_f32_16x16x32_bf16 v[82:85], v[246:249], v[214:217], v[82:85]
	v_mfma_f32_16x16x32_bf16 v[78:81], v[238:241], v[222:225], v[78:81]
	v_mfma_f32_16x16x32_bf16 v[74:77], v[246:249], v[222:225], v[74:77]
	v_mfma_f32_16x16x32_bf16 v[70:73], v[238:241], v[230:233], v[70:73]
	v_mfma_f32_16x16x32_bf16 v[66:69], v[246:249], v[230:233], v[66:69]
	v_mfma_f32_16x16x32_bf16 v[168:171], v[250:253], v[178:181], v[90:93]
	v_mfma_f32_16x16x32_bf16 v[178:181], v[242:245], v[218:221], v[86:89]
	v_mfma_f32_16x16x32_bf16 v[214:217], v[250:253], v[218:221], v[82:85]
	v_mfma_f32_16x16x32_bf16 v[218:221], v[242:245], v[226:229], v[78:81]
	v_mfma_f32_16x16x32_bf16 v[222:225], v[250:253], v[226:229], v[74:77]
	v_mfma_f32_16x16x32_bf16 v[226:229], v[242:245], v[234:237], v[70:73]
	v_mfma_f32_16x16x32_bf16 v[230:233], v[250:253], v[234:237], v[66:69]
	s_setprio 0
	s_barrier
	s_nop 0
	ds_read_b128 v[66:69], v176 offset:16384
	ds_read_b128 v[70:73], v176 offset:17408
	ds_read_b128 v[74:77], v139 offset:18432
	ds_read_b128 v[78:81], v139 offset:19456
	ds_read_b128 v[82:85], v139 offset:20480
	ds_read_b128 v[86:89], v139 offset:21504
	ds_read_b128 v[90:93], v139 offset:22528
	ds_read_b128 v[94:97], v139 offset:23552
	s_waitcnt vmcnt(4)
	s_barrier
	s_waitcnt lgkmcnt(0)
	s_setprio 1
	s_waitcnt lgkmcnt(0)
	v_mfma_f32_16x16x32_bf16 v[62:65], v[134:137], v[66:69], v[62:65]
	v_mfma_f32_16x16x32_bf16 v[58:61], v[160:163], v[66:69], v[58:61]
	v_mfma_f32_16x16x32_bf16 v[54:57], v[134:137], v[74:77], v[54:57]
	v_mfma_f32_16x16x32_bf16 v[50:53], v[160:163], v[74:77], v[50:53]
	v_mfma_f32_16x16x32_bf16 v[46:49], v[134:137], v[82:85], v[46:49]
	v_mfma_f32_16x16x32_bf16 v[42:45], v[160:163], v[82:85], v[42:45]
	v_mfma_f32_16x16x32_bf16 v[38:41], v[134:137], v[90:93], v[38:41]
	v_mfma_f32_16x16x32_bf16 v[34:37], v[160:163], v[90:93], v[34:37]
	v_mfma_f32_16x16x32_bf16 v[62:65], v[154:157], v[70:73], v[62:65]
	v_mfma_f32_16x16x32_bf16 v[58:61], v[164:167], v[70:73], v[58:61]
	v_mfma_f32_16x16x32_bf16 v[54:57], v[154:157], v[78:81], v[54:57]
	v_mfma_f32_16x16x32_bf16 v[50:53], v[164:167], v[78:81], v[50:53]
	v_mfma_f32_16x16x32_bf16 v[46:49], v[154:157], v[86:89], v[46:49]
	v_mfma_f32_16x16x32_bf16 v[42:45], v[164:167], v[86:89], v[42:45]
	v_mfma_f32_16x16x32_bf16 v[38:41], v[154:157], v[94:97], v[38:41]
	v_mfma_f32_16x16x32_bf16 v[34:37], v[164:167], v[94:97], v[34:37]
	s_setprio 0
	s_setprio 1
	v_mfma_f32_16x16x32_bf16 v[30:33], v[238:241], v[66:69], v[30:33]
	v_mfma_f32_16x16x32_bf16 v[26:29], v[246:249], v[66:69], v[26:29]
	v_mfma_f32_16x16x32_bf16 v[22:25], v[238:241], v[74:77], v[22:25]
	v_mfma_f32_16x16x32_bf16 v[18:21], v[246:249], v[74:77], v[18:21]
	v_mfma_f32_16x16x32_bf16 v[12:15], v[238:241], v[82:85], v[12:15]
	v_mfma_f32_16x16x32_bf16 v[8:11], v[246:249], v[82:85], v[8:11]
	v_mfma_f32_16x16x32_bf16 v[4:7], v[238:241], v[90:93], v[4:7]
	v_mfma_f32_16x16x32_bf16 v[0:3], v[246:249], v[90:93], v[0:3]
	v_mfma_f32_16x16x32_bf16 v[134:137], v[242:245], v[70:73], v[30:33]
	v_mfma_f32_16x16x32_bf16 v[154:157], v[250:253], v[70:73], v[26:29]
	v_mfma_f32_16x16x32_bf16 v[160:163], v[242:245], v[78:81], v[22:25]
	v_mfma_f32_16x16x32_bf16 v[164:167], v[250:253], v[78:81], v[18:21]
	v_mfma_f32_16x16x32_bf16 v[234:237], v[242:245], v[86:89], v[12:15]
	v_mfma_f32_16x16x32_bf16 v[82:85], v[250:253], v[86:89], v[8:11]
	v_mfma_f32_16x16x32_bf16 v[238:241], v[242:245], v[94:97], v[4:7]
	v_mfma_f32_16x16x32_bf16 v[242:245], v[250:253], v[94:97], v[0:3]
	s_setprio 0
	s_nop 1
	v_add3_u32 v0, s2, v153, v138
	s_barrier
	ds_read_b128 v[246:249], v0
	ds_read_b128 v[250:253], v0 offset:1024
	ds_read_b128 v[200:203], v0 offset:2048
	ds_read_b128 v[172:175], v0 offset:3072
	ds_read_b128 v[4:7], v176 offset:32768
	ds_read_b128 v[8:11], v176 offset:33792
	ds_read_b128 v[12:15], v139 offset:34816
	ds_read_b128 v[18:21], v139 offset:35840
	ds_read_b128 v[22:25], v139 offset:36864
	ds_read_b128 v[26:29], v139 offset:37888
	ds_read_b128 v[30:33], v139 offset:38912
	ds_read_b128 v[208:211], v139 offset:39936
	s_waitcnt vmcnt(2)
	s_barrier
	s_waitcnt lgkmcnt(0)
	s_setprio 1
	s_waitcnt lgkmcnt(0)
	v_mfma_f32_16x16x32_bf16 v[0:3], v[246:249], v[4:7], v[126:129]
	v_mfma_f32_16x16x32_bf16 v[126:129], v[250:253], v[8:11], v[0:3]
	v_mfma_f32_16x16x32_bf16 v[0:3], v[200:203], v[4:7], v[122:125]
	v_mfma_f32_16x16x32_bf16 v[122:125], v[172:175], v[8:11], v[0:3]
	v_mfma_f32_16x16x32_bf16 v[0:3], v[246:249], v[12:15], v[118:121]
	v_mfma_f32_16x16x32_bf16 v[90:93], v[250:253], v[18:21], v[0:3]
	v_mfma_f32_16x16x32_bf16 v[0:3], v[200:203], v[12:15], v[114:117]
	v_mfma_f32_16x16x32_bf16 v[94:97], v[172:175], v[18:21], v[0:3]
	v_mfma_f32_16x16x32_bf16 v[0:3], v[246:249], v[22:25], v[110:113]
	v_mfma_f32_16x16x32_bf16 v[74:77], v[250:253], v[26:29], v[0:3]
	v_mfma_f32_16x16x32_bf16 v[0:3], v[200:203], v[22:25], v[106:109]
	v_mfma_f32_16x16x32_bf16 v[86:89], v[172:175], v[26:29], v[0:3]
	v_mfma_f32_16x16x32_bf16 v[0:3], v[246:249], v[30:33], v[102:105]
	v_mfma_f32_16x16x32_bf16 v[196:199], v[250:253], v[208:211], v[0:3]
	v_mfma_f32_16x16x32_bf16 v[0:3], v[200:203], v[30:33], v[98:101]
	v_mfma_f32_16x16x32_bf16 v[78:81], v[172:175], v[208:211], v[0:3]
	s_setprio 0
	v_add3_u32 v70, s91, v153, v138
	s_barrier
	ds_read_b128 v[204:207], v70
	s_nop 2
	ds_read_b128 v[0:3], v70 offset:1024
	ds_read_b128 v[66:69], v70 offset:2048
	ds_read_b128 v[70:73], v70 offset:3072
	s_waitcnt vmcnt(0)
	s_barrier
	s_waitcnt lgkmcnt(0)
	s_setprio 1
	s_waitcnt lgkmcnt(0)
	v_mfma_f32_16x16x32_bf16 v[98:101], v[204:207], v[4:7], v[182:185]
	v_mfma_f32_16x16x32_bf16 v[4:7], v[66:69], v[4:7], v[168:171]
	v_mfma_f32_16x16x32_bf16 v[98:101], v[0:3], v[8:11], v[98:101]
	v_mfma_f32_16x16x32_bf16 v[102:105], v[70:73], v[8:11], v[4:7]
	v_mfma_f32_16x16x32_bf16 v[8:11], v[204:207], v[12:15], v[178:181]
	v_mfma_f32_16x16x32_bf16 v[12:15], v[66:69], v[12:15], v[214:217]
	v_mfma_f32_16x16x32_bf16 v[8:11], v[0:3], v[18:21], v[8:11]
	v_mfma_f32_16x16x32_bf16 v[12:15], v[70:73], v[18:21], v[12:15]
	v_mfma_f32_16x16x32_bf16 v[18:21], v[204:207], v[22:25], v[218:221]
	v_mfma_f32_16x16x32_bf16 v[22:25], v[66:69], v[22:25], v[222:225]
	v_mfma_f32_16x16x32_bf16 v[18:21], v[0:3], v[26:29], v[18:21]
	v_mfma_f32_16x16x32_bf16 v[22:25], v[70:73], v[26:29], v[22:25]
	v_mfma_f32_16x16x32_bf16 v[26:29], v[204:207], v[30:33], v[226:229]
	v_mfma_f32_16x16x32_bf16 v[30:33], v[66:69], v[30:33], v[230:233]
	v_mfma_f32_16x16x32_bf16 v[26:29], v[0:3], v[208:211], v[26:29]
	v_mfma_f32_16x16x32_bf16 v[30:33], v[70:73], v[208:211], v[30:33]
	s_setprio 0
	s_barrier
	ds_read_b128 v[168:171], v176 offset:49152
	ds_read_b128 v[178:181], v176 offset:50176
	ds_read_b128 v[208:211], v139 offset:51200
	ds_read_b128 v[214:217], v139 offset:52224
	ds_read_b128 v[218:221], v139 offset:53248
	ds_read_b128 v[222:225], v139 offset:54272
	ds_read_b128 v[226:229], v139 offset:55296
	ds_read_b128 v[230:233], v139 offset:56320
	s_barrier
	s_waitcnt lgkmcnt(0)
	s_setprio 1
	s_waitcnt lgkmcnt(0)
	v_mfma_f32_16x16x32_bf16 v[62:65], v[246:249], v[168:171], v[62:65]
	v_mfma_f32_16x16x32_bf16 v[58:61], v[200:203], v[168:171], v[58:61]
	v_mfma_f32_16x16x32_bf16 v[54:57], v[246:249], v[208:211], v[54:57]
	v_mfma_f32_16x16x32_bf16 v[50:53], v[200:203], v[208:211], v[50:53]
	v_mfma_f32_16x16x32_bf16 v[46:49], v[246:249], v[218:221], v[46:49]
	v_mfma_f32_16x16x32_bf16 v[42:45], v[200:203], v[218:221], v[42:45]
	v_mfma_f32_16x16x32_bf16 v[38:41], v[246:249], v[226:229], v[38:41]
	v_mfma_f32_16x16x32_bf16 v[34:37], v[200:203], v[226:229], v[34:37]
	v_mfma_f32_16x16x32_bf16 v[4:7], v[250:253], v[178:181], v[62:65]
	v_mfma_f32_16x16x32_bf16 v[182:185], v[172:175], v[178:181], v[58:61]
	v_mfma_f32_16x16x32_bf16 v[114:117], v[250:253], v[214:217], v[54:57]
	v_mfma_f32_16x16x32_bf16 v[118:121], v[172:175], v[214:217], v[50:53]
	v_mfma_f32_16x16x32_bf16 v[106:109], v[250:253], v[222:225], v[46:49]
	v_mfma_f32_16x16x32_bf16 v[110:113], v[172:175], v[222:225], v[42:45]
	v_mfma_f32_16x16x32_bf16 v[246:249], v[250:253], v[230:233], v[38:41]
	v_mfma_f32_16x16x32_bf16 v[250:253], v[172:175], v[230:233], v[34:37]
	s_setprio 0
	s_setprio 1
	v_mfma_f32_16x16x32_bf16 v[34:37], v[204:207], v[168:171], v[134:137]
	v_mfma_f32_16x16x32_bf16 v[42:45], v[204:207], v[208:211], v[160:163]
	v_mfma_f32_16x16x32_bf16 v[50:53], v[204:207], v[218:221], v[234:237]
	v_mfma_f32_16x16x32_bf16 v[58:61], v[204:207], v[226:229], v[238:241]
	v_mfma_f32_16x16x32_bf16 v[34:37], v[0:3], v[178:181], v[34:37]
	v_mfma_f32_16x16x32_bf16 v[38:41], v[66:69], v[168:171], v[154:157]
	v_mfma_f32_16x16x32_bf16 v[42:45], v[0:3], v[214:217], v[42:45]
	v_mfma_f32_16x16x32_bf16 v[46:49], v[66:69], v[208:211], v[164:167]
	v_mfma_f32_16x16x32_bf16 v[50:53], v[0:3], v[222:225], v[50:53]
	v_mfma_f32_16x16x32_bf16 v[54:57], v[66:69], v[218:221], v[82:85]
	v_mfma_f32_16x16x32_bf16 v[58:61], v[0:3], v[230:233], v[58:61]
	v_mfma_f32_16x16x32_bf16 v[0:3], v[66:69], v[226:229], v[242:245]
	v_mfma_f32_16x16x32_bf16 v[38:41], v[70:73], v[178:181], v[38:41]
	v_mfma_f32_16x16x32_bf16 v[46:49], v[70:73], v[214:217], v[46:49]
	v_mfma_f32_16x16x32_bf16 v[54:57], v[70:73], v[222:225], v[54:57]
	v_mfma_f32_16x16x32_bf16 v[62:65], v[70:73], v[230:233], v[0:3]
	s_setprio 0
	s_movk_i32 s0, 0x100
	v_cmp_gt_u32_e32 vcc, s0, v150
	s_barrier
	s_and_saveexec_b64 s[6:7], vcc
	s_cbranch_execz .LBB0_228
	s_barrier
	s_nop 0

.LBB0_317:
	s_mov_b64 s[36:37], 0
	s_mov_b64 s[34:35], 0
	s_mov_b64 s[6:7], 0x80
	s_mov_b64 s[8:9], 8
	s_mov_b32 s62, 0
	s_branch .LBB0_301
	s_nop 0

.LBB0_526:
	ds_read_b128 v[144:147], v136
	ds_read_b128 v[148:151], v136 offset:1024
	ds_read_b128 v[152:155], v136 offset:2048
	ds_read_b128 v[156:159], v136 offset:3072
	s_add_i32 s35, s15, s34
	s_add_i32 s36, s35, 0x80080
	s_mov_b32 m0, s7
	ds_read_b128 v[160:163], v137
	ds_read_b128 v[164:167], v137 offset:1024
	ds_read_b128 v[168:171], v138
	ds_read_b128 v[172:175], v138 offset:1024
	ds_read_b128 v[178:181], v139
	ds_read_b128 v[182:185], v139 offset:1024
	ds_read_b128 v[196:199], v140
	ds_read_b128 v[200:203], v140 offset:1024
	buffer_load_dwordx4 v134, s[48:51], s36 offen lds
	s_mov_b32 m0, s6
	s_nop 0
	buffer_load_dwordx4 v135, s[48:51], s36 offen lds
	s_waitcnt lgkmcnt(8)
	s_barrier
	s_waitcnt lgkmcnt(0)
	s_setprio 1
	s_waitcnt lgkmcnt(7)
	v_mfma_f32_16x16x32_bf16 v[126:129], v[144:147], v[160:163], v[126:129]
	v_mfma_f32_16x16x32_bf16 v[122:125], v[152:155], v[160:163], v[122:125]
	s_waitcnt lgkmcnt(5)
	v_mfma_f32_16x16x32_bf16 v[118:121], v[144:147], v[168:171], v[118:121]
	v_mfma_f32_16x16x32_bf16 v[114:117], v[152:155], v[168:171], v[114:117]
	s_waitcnt lgkmcnt(3)
	v_mfma_f32_16x16x32_bf16 v[110:113], v[144:147], v[178:181], v[110:113]
	v_mfma_f32_16x16x32_bf16 v[106:109], v[152:155], v[178:181], v[106:109]
	s_waitcnt lgkmcnt(1)
	v_mfma_f32_16x16x32_bf16 v[102:105], v[144:147], v[196:199], v[102:105]
	v_mfma_f32_16x16x32_bf16 v[98:101], v[152:155], v[196:199], v[98:101]
	v_mfma_f32_16x16x32_bf16 v[126:129], v[148:151], v[164:167], v[126:129]
	v_mfma_f32_16x16x32_bf16 v[122:125], v[156:159], v[164:167], v[122:125]
	v_mfma_f32_16x16x32_bf16 v[118:121], v[148:151], v[172:175], v[118:121]
	v_mfma_f32_16x16x32_bf16 v[114:117], v[156:159], v[172:175], v[114:117]
	v_mfma_f32_16x16x32_bf16 v[110:113], v[148:151], v[182:185], v[110:113]
	v_mfma_f32_16x16x32_bf16 v[106:109], v[156:159], v[182:185], v[106:109]
	s_waitcnt lgkmcnt(0)
	v_mfma_f32_16x16x32_bf16 v[102:105], v[148:151], v[200:203], v[102:105]
	v_mfma_f32_16x16x32_bf16 v[98:101], v[156:159], v[200:203], v[98:101]
	s_setprio 0
	s_barrier
	s_add_i32 s36, s16, s34
	s_add_i32 s37, s36, 0x100
	s_mov_b32 m0, s18
	ds_read_b128 v[204:207], v141
	ds_read_b128 v[208:211], v141 offset:1024
	ds_read_b128 v[214:217], v141 offset:2048
	ds_read_b128 v[218:221], v141 offset:3072
	buffer_load_dwordx4 v134, s[52:55], s37 offen lds
	s_mov_b32 m0, s19
	s_nop 0
	buffer_load_dwordx4 v135, s[52:55], s37 offen lds
	s_barrier
	s_waitcnt lgkmcnt(0)
	s_setprio 1
	s_waitcnt lgkmcnt(3)
	v_mfma_f32_16x16x32_bf16 v[94:97], v[204:207], v[160:163], v[94:97]
	s_waitcnt lgkmcnt(1)
	v_mfma_f32_16x16x32_bf16 v[90:93], v[214:217], v[160:163], v[90:93]
	v_mfma_f32_16x16x32_bf16 v[86:89], v[204:207], v[168:171], v[86:89]
	v_mfma_f32_16x16x32_bf16 v[82:85], v[214:217], v[168:171], v[82:85]
	v_mfma_f32_16x16x32_bf16 v[78:81], v[204:207], v[178:181], v[78:81]
	v_mfma_f32_16x16x32_bf16 v[74:77], v[214:217], v[178:181], v[74:77]
	v_mfma_f32_16x16x32_bf16 v[70:73], v[204:207], v[196:199], v[70:73]
	v_mfma_f32_16x16x32_bf16 v[66:69], v[214:217], v[196:199], v[66:69]
	v_mfma_f32_16x16x32_bf16 v[94:97], v[208:211], v[164:167], v[94:97]
	s_waitcnt lgkmcnt(0)
	v_mfma_f32_16x16x32_bf16 v[90:93], v[218:221], v[164:167], v[90:93]
	v_mfma_f32_16x16x32_bf16 v[86:89], v[208:211], v[172:175], v[86:89]
	v_mfma_f32_16x16x32_bf16 v[82:85], v[218:221], v[172:175], v[82:85]
	v_mfma_f32_16x16x32_bf16 v[78:81], v[208:211], v[182:185], v[78:81]
	v_mfma_f32_16x16x32_bf16 v[74:77], v[218:221], v[182:185], v[74:77]
	v_mfma_f32_16x16x32_bf16 v[70:73], v[208:211], v[200:203], v[70:73]
	v_mfma_f32_16x16x32_bf16 v[66:69], v[218:221], v[200:203], v[66:69]
	s_setprio 0
	s_add_i32 s37, s35, 0x100
	s_mov_b32 m0, s17
	s_barrier
	ds_read_b128 v[160:163], v137 offset:16384
	ds_read_b128 v[164:167], v137 offset:17408
	ds_read_b128 v[168:171], v138 offset:16384
	ds_read_b128 v[172:175], v138 offset:17408
	ds_read_b128 v[178:181], v139 offset:16384
	ds_read_b128 v[182:185], v139 offset:17408
	ds_read_b128 v[196:199], v140 offset:16384
	ds_read_b128 v[200:203], v140 offset:17408
	buffer_load_dwordx4 v134, s[48:51], s37 offen lds
	s_mov_b32 m0, s20
	s_nop 0
	buffer_load_dwordx4 v135, s[48:51], s37 offen lds
	s_barrier
	s_waitcnt lgkmcnt(0)
	s_setprio 1
	s_waitcnt lgkmcnt(7)
	v_mfma_f32_16x16x32_bf16 v[62:65], v[144:147], v[160:163], v[62:65]
	v_mfma_f32_16x16x32_bf16 v[58:61], v[152:155], v[160:163], v[58:61]
	s_waitcnt lgkmcnt(5)
	v_mfma_f32_16x16x32_bf16 v[54:57], v[144:147], v[168:171], v[54:57]
	v_mfma_f32_16x16x32_bf16 v[50:53], v[152:155], v[168:171], v[50:53]
	s_waitcnt lgkmcnt(3)
	v_mfma_f32_16x16x32_bf16 v[46:49], v[144:147], v[178:181], v[46:49]
	v_mfma_f32_16x16x32_bf16 v[42:45], v[152:155], v[178:181], v[42:45]
	s_waitcnt lgkmcnt(1)
	v_mfma_f32_16x16x32_bf16 v[38:41], v[144:147], v[196:199], v[38:41]
	v_mfma_f32_16x16x32_bf16 v[34:37], v[152:155], v[196:199], v[34:37]
	v_mfma_f32_16x16x32_bf16 v[62:65], v[148:151], v[164:167], v[62:65]
	v_mfma_f32_16x16x32_bf16 v[58:61], v[156:159], v[164:167], v[58:61]
	v_mfma_f32_16x16x32_bf16 v[54:57], v[148:151], v[172:175], v[54:57]
	v_mfma_f32_16x16x32_bf16 v[50:53], v[156:159], v[172:175], v[50:53]
	v_mfma_f32_16x16x32_bf16 v[46:49], v[148:151], v[182:185], v[46:49]
	v_mfma_f32_16x16x32_bf16 v[42:45], v[156:159], v[182:185], v[42:45]
	s_waitcnt lgkmcnt(0)
	v_mfma_f32_16x16x32_bf16 v[38:41], v[148:151], v[200:203], v[38:41]
	v_mfma_f32_16x16x32_bf16 v[34:37], v[156:159], v[200:203], v[34:37]
	s_setprio 0
	s_barrier
	s_add_i32 s37, s36, 0x80100
	s_mov_b32 m0, s21
	s_nop 0
	buffer_load_dwordx4 v134, s[52:55], s37 offen lds
	s_mov_b32 m0, s22
	s_nop 0
	buffer_load_dwordx4 v135, s[52:55], s37 offen lds
	s_waitcnt vmcnt(6)
	s_barrier
	s_setprio 1
	v_mfma_f32_16x16x32_bf16 v[30:33], v[204:207], v[160:163], v[30:33]
	v_mfma_f32_16x16x32_bf16 v[26:29], v[214:217], v[160:163], v[26:29]
	v_mfma_f32_16x16x32_bf16 v[22:25], v[204:207], v[168:171], v[22:25]
	v_mfma_f32_16x16x32_bf16 v[18:21], v[214:217], v[168:171], v[18:21]
	v_mfma_f32_16x16x32_bf16 v[12:15], v[204:207], v[178:181], v[12:15]
	v_mfma_f32_16x16x32_bf16 v[8:11], v[214:217], v[178:181], v[8:11]
	v_mfma_f32_16x16x32_bf16 v[4:7], v[204:207], v[196:199], v[4:7]
	v_mfma_f32_16x16x32_bf16 v[0:3], v[214:217], v[196:199], v[0:3]
	v_mfma_f32_16x16x32_bf16 v[30:33], v[208:211], v[164:167], v[30:33]
	v_mfma_f32_16x16x32_bf16 v[26:29], v[218:221], v[164:167], v[26:29]
	v_mfma_f32_16x16x32_bf16 v[22:25], v[208:211], v[172:175], v[22:25]
	v_mfma_f32_16x16x32_bf16 v[18:21], v[218:221], v[172:175], v[18:21]
	v_mfma_f32_16x16x32_bf16 v[12:15], v[208:211], v[182:185], v[12:15]
	v_mfma_f32_16x16x32_bf16 v[8:11], v[218:221], v[182:185], v[8:11]
	v_mfma_f32_16x16x32_bf16 v[4:7], v[208:211], v[200:203], v[4:7]
	v_mfma_f32_16x16x32_bf16 v[0:3], v[218:221], v[200:203], v[0:3]
	s_setprio 0
	s_barrier
	ds_read_b128 v[144:147], v142
	ds_read_b128 v[148:151], v142 offset:1024
	ds_read_b128 v[152:155], v142 offset:2048
	ds_read_b128 v[156:159], v142 offset:3072
	s_add_i32 s37, s35, 0x80100
	s_mov_b32 m0, s23
	ds_read_b128 v[160:163], v137 offset:32768
	ds_read_b128 v[164:167], v137 offset:33792
	ds_read_b128 v[168:171], v138 offset:32768
	ds_read_b128 v[172:175], v138 offset:33792
	ds_read_b128 v[178:181], v139 offset:32768
	ds_read_b128 v[182:185], v139 offset:33792
	ds_read_b128 v[196:199], v140 offset:32768
	ds_read_b128 v[200:203], v140 offset:33792
	buffer_load_dwordx4 v134, s[48:51], s37 offen lds
	s_mov_b32 m0, s24
	s_nop 0
	buffer_load_dwordx4 v135, s[48:51], s37 offen lds
	s_waitcnt lgkmcnt(8)
	s_barrier
	s_waitcnt lgkmcnt(0)
	s_setprio 1
	s_waitcnt lgkmcnt(7)
	v_mfma_f32_16x16x32_bf16 v[126:129], v[144:147], v[160:163], v[126:129]
	v_mfma_f32_16x16x32_bf16 v[122:125], v[152:155], v[160:163], v[122:125]
	s_waitcnt lgkmcnt(5)
	v_mfma_f32_16x16x32_bf16 v[118:121], v[144:147], v[168:171], v[118:121]
	v_mfma_f32_16x16x32_bf16 v[114:117], v[152:155], v[168:171], v[114:117]
	s_waitcnt lgkmcnt(3)
	v_mfma_f32_16x16x32_bf16 v[110:113], v[144:147], v[178:181], v[110:113]
	v_mfma_f32_16x16x32_bf16 v[106:109], v[152:155], v[178:181], v[106:109]
	s_waitcnt lgkmcnt(1)
	v_mfma_f32_16x16x32_bf16 v[102:105], v[144:147], v[196:199], v[102:105]
	v_mfma_f32_16x16x32_bf16 v[98:101], v[152:155], v[196:199], v[98:101]
	v_mfma_f32_16x16x32_bf16 v[126:129], v[148:151], v[164:167], v[126:129]
	v_mfma_f32_16x16x32_bf16 v[122:125], v[156:159], v[164:167], v[122:125]
	v_mfma_f32_16x16x32_bf16 v[118:121], v[148:151], v[172:175], v[118:121]
	v_mfma_f32_16x16x32_bf16 v[114:117], v[156:159], v[172:175], v[114:117]
	v_mfma_f32_16x16x32_bf16 v[110:113], v[148:151], v[182:185], v[110:113]
	v_mfma_f32_16x16x32_bf16 v[106:109], v[156:159], v[182:185], v[106:109]
	s_waitcnt lgkmcnt(0)
	v_mfma_f32_16x16x32_bf16 v[102:105], v[148:151], v[200:203], v[102:105]
	v_mfma_f32_16x16x32_bf16 v[98:101], v[156:159], v[200:203], v[98:101]
	s_setprio 0
	s_barrier
	s_add_i32 s37, s36, 0x180
	s_mov_b32 m0, s25
	ds_read_b128 v[204:207], v143
	ds_read_b128 v[208:211], v143 offset:1024
	ds_read_b128 v[214:217], v143 offset:2048
	ds_read_b128 v[218:221], v143 offset:3072
	buffer_load_dwordx4 v134, s[52:55], s37 offen lds
	s_mov_b32 m0, s26
	s_nop 0
	buffer_load_dwordx4 v135, s[52:55], s37 offen lds
	s_barrier
	s_waitcnt lgkmcnt(0)
	s_setprio 1
	s_waitcnt lgkmcnt(3)
	v_mfma_f32_16x16x32_bf16 v[94:97], v[204:207], v[160:163], v[94:97]
	s_waitcnt lgkmcnt(1)
	v_mfma_f32_16x16x32_bf16 v[90:93], v[214:217], v[160:163], v[90:93]
	v_mfma_f32_16x16x32_bf16 v[86:89], v[204:207], v[168:171], v[86:89]
	v_mfma_f32_16x16x32_bf16 v[82:85], v[214:217], v[168:171], v[82:85]
	v_mfma_f32_16x16x32_bf16 v[78:81], v[204:207], v[178:181], v[78:81]
	v_mfma_f32_16x16x32_bf16 v[74:77], v[214:217], v[178:181], v[74:77]
	v_mfma_f32_16x16x32_bf16 v[70:73], v[204:207], v[196:199], v[70:73]
	v_mfma_f32_16x16x32_bf16 v[66:69], v[214:217], v[196:199], v[66:69]
	v_mfma_f32_16x16x32_bf16 v[94:97], v[208:211], v[164:167], v[94:97]
	s_waitcnt lgkmcnt(0)
	v_mfma_f32_16x16x32_bf16 v[90:93], v[218:221], v[164:167], v[90:93]
	v_mfma_f32_16x16x32_bf16 v[86:89], v[208:211], v[172:175], v[86:89]
	v_mfma_f32_16x16x32_bf16 v[82:85], v[218:221], v[172:175], v[82:85]
	v_mfma_f32_16x16x32_bf16 v[78:81], v[208:211], v[182:185], v[78:81]
	v_mfma_f32_16x16x32_bf16 v[74:77], v[218:221], v[182:185], v[74:77]
	v_mfma_f32_16x16x32_bf16 v[70:73], v[208:211], v[200:203], v[70:73]
	v_mfma_f32_16x16x32_bf16 v[66:69], v[218:221], v[200:203], v[66:69]
	s_setprio 0
	s_addk_i32 s35, 0x180
	s_mov_b32 m0, s27
	s_barrier
	ds_read_b128 v[160:163], v137 offset:49152
	ds_read_b128 v[164:167], v137 offset:50176
	ds_read_b128 v[168:171], v138 offset:49152
	ds_read_b128 v[172:175], v138 offset:50176
	ds_read_b128 v[178:181], v139 offset:49152
	ds_read_b128 v[182:185], v139 offset:50176
	ds_read_b128 v[196:199], v140 offset:49152
	ds_read_b128 v[200:203], v140 offset:50176
	buffer_load_dwordx4 v134, s[48:51], s35 offen lds
	s_mov_b32 m0, s28
	s_nop 0
	buffer_load_dwordx4 v135, s[48:51], s35 offen lds
	s_barrier
	s_waitcnt lgkmcnt(0)
	s_setprio 1
	s_waitcnt lgkmcnt(7)
	v_mfma_f32_16x16x32_bf16 v[62:65], v[144:147], v[160:163], v[62:65]
	v_mfma_f32_16x16x32_bf16 v[58:61], v[152:155], v[160:163], v[58:61]
	s_waitcnt lgkmcnt(5)
	v_mfma_f32_16x16x32_bf16 v[54:57], v[144:147], v[168:171], v[54:57]
	v_mfma_f32_16x16x32_bf16 v[50:53], v[152:155], v[168:171], v[50:53]
	s_waitcnt lgkmcnt(3)
	v_mfma_f32_16x16x32_bf16 v[46:49], v[144:147], v[178:181], v[46:49]
	v_mfma_f32_16x16x32_bf16 v[42:45], v[152:155], v[178:181], v[42:45]
	s_waitcnt lgkmcnt(1)
	v_mfma_f32_16x16x32_bf16 v[38:41], v[144:147], v[196:199], v[38:41]
	v_mfma_f32_16x16x32_bf16 v[34:37], v[152:155], v[196:199], v[34:37]
	v_mfma_f32_16x16x32_bf16 v[62:65], v[148:151], v[164:167], v[62:65]
	v_mfma_f32_16x16x32_bf16 v[58:61], v[156:159], v[164:167], v[58:61]
	v_mfma_f32_16x16x32_bf16 v[54:57], v[148:151], v[172:175], v[54:57]
	v_mfma_f32_16x16x32_bf16 v[50:53], v[156:159], v[172:175], v[50:53]
	v_mfma_f32_16x16x32_bf16 v[46:49], v[148:151], v[182:185], v[46:49]
	v_mfma_f32_16x16x32_bf16 v[42:45], v[156:159], v[182:185], v[42:45]
	s_waitcnt lgkmcnt(0)
	v_mfma_f32_16x16x32_bf16 v[38:41], v[148:151], v[200:203], v[38:41]
	v_mfma_f32_16x16x32_bf16 v[34:37], v[156:159], v[200:203], v[34:37]
	s_setprio 0
	s_barrier
	s_add_i32 s36, s36, 0x80180
	s_mov_b32 m0, s29
	s_nop 0
	buffer_load_dwordx4 v134, s[52:55], s36 offen lds
	s_mov_b32 m0, s30
	s_nop 0
	buffer_load_dwordx4 v135, s[52:55], s36 offen lds
	s_waitcnt vmcnt(6)
	s_barrier
	s_setprio 1
	v_mfma_f32_16x16x32_bf16 v[30:33], v[204:207], v[160:163], v[30:33]
	v_mfma_f32_16x16x32_bf16 v[26:29], v[214:217], v[160:163], v[26:29]
	v_mfma_f32_16x16x32_bf16 v[22:25], v[204:207], v[168:171], v[22:25]
	v_mfma_f32_16x16x32_bf16 v[18:21], v[214:217], v[168:171], v[18:21]
	v_mfma_f32_16x16x32_bf16 v[12:15], v[204:207], v[178:181], v[12:15]
	v_mfma_f32_16x16x32_bf16 v[8:11], v[214:217], v[178:181], v[8:11]
	v_mfma_f32_16x16x32_bf16 v[4:7], v[204:207], v[196:199], v[4:7]
	v_mfma_f32_16x16x32_bf16 v[0:3], v[214:217], v[196:199], v[0:3]
	v_mfma_f32_16x16x32_bf16 v[30:33], v[208:211], v[164:167], v[30:33]
	v_mfma_f32_16x16x32_bf16 v[26:29], v[218:221], v[164:167], v[26:29]
	v_mfma_f32_16x16x32_bf16 v[22:25], v[208:211], v[172:175], v[22:25]
	v_mfma_f32_16x16x32_bf16 v[18:21], v[218:221], v[172:175], v[18:21]
	v_mfma_f32_16x16x32_bf16 v[12:15], v[208:211], v[182:185], v[12:15]
	v_mfma_f32_16x16x32_bf16 v[8:11], v[218:221], v[182:185], v[8:11]
	v_mfma_f32_16x16x32_bf16 v[4:7], v[208:211], v[200:203], v[4:7]
	v_mfma_f32_16x16x32_bf16 v[0:3], v[218:221], v[200:203], v[0:3]
	s_setprio 0
	s_add_i32 s31, s31, 2
	s_addk_i32 s34, 0x100
	s_cmp_lt_u32 s31, 28
	s_barrier
	s_cbranch_scc1 .LBB0_526
	v_mov_b32_e32 v144, v130
	s_or_b32 s15, s15, 0x80f80
	v_and_b32_e32 v147, 15, v144
	v_bfe_u32 v146, v144, 4, 2
	v_lshlrev_b32_e32 v150, 2, v144
	v_bfe_u32 v145, v144, 6, 2
	v_lshlrev_b32_e32 v174, 4, v146
	v_lshlrev_b32_e32 v148, 6, v147
	v_and_b32_e32 v175, 32, v150
	v_lshlrev_b32_e32 v149, 12, v145
	v_bitop3_b32 v176, v174, v175, v148 bitop3:0x36
	v_add3_u32 v148, s78, v176, v149
	ds_read_b128 v[150:153], v148
	ds_read_b128 v[154:157], v148 offset:1024
	ds_read_b128 v[158:161], v148 offset:2048
	ds_read_b128 v[162:165], v148 offset:3072
	v_ashrrev_i32_e32 v148, 2, v144
	v_lshlrev_b32_e32 v178, 6, v144
	v_and_b32_e32 v148, 0xffffffc0, v148
	v_and_b32_e32 v178, 0x3c0, v178
	v_lshlrev_b32_e32 v177, 7, v148
	v_bitop3_b32 v174, v178, v175, v174 bitop3:0x36
	s_waitcnt vmcnt(0)
	v_add3_u32 v190, 0, v176, v177
	v_add3_u32 v174, 0, v174, v177
	s_mov_b32 m0, s7
	ds_read_b128 v[166:169], v190
	ds_read_b128 v[170:173], v190 offset:1024
	ds_read_b128 v[178:181], v174 offset:2048
	ds_read_b128 v[182:185], v174 offset:3072
	ds_read_b128 v[196:199], v174 offset:4096
	ds_read_b128 v[200:203], v174 offset:5120
	ds_read_b128 v[204:207], v174 offset:6144
	ds_read_b128 v[208:211], v174 offset:7168
	buffer_load_dwordx4 v134, s[48:51], s15 offen lds
	s_mov_b32 m0, s6
	s_nop 0
	buffer_load_dwordx4 v135, s[48:51], s15 offen lds
	s_barrier
	s_waitcnt lgkmcnt(0)
	s_setprio 1
	s_waitcnt lgkmcnt(7)
	v_mfma_f32_16x16x32_bf16 v[126:129], v[150:153], v[166:169], v[126:129]
	v_mfma_f32_16x16x32_bf16 v[122:125], v[158:161], v[166:169], v[122:125]
	s_waitcnt lgkmcnt(5)
	v_mfma_f32_16x16x32_bf16 v[118:121], v[150:153], v[178:181], v[118:121]
	v_mfma_f32_16x16x32_bf16 v[114:117], v[158:161], v[178:181], v[114:117]
	s_waitcnt lgkmcnt(1)
	v_mfma_f32_16x16x32_bf16 v[102:105], v[150:153], v[204:207], v[102:105]
	v_mfma_f32_16x16x32_bf16 v[98:101], v[158:161], v[204:207], v[98:101]
	v_mfma_f32_16x16x32_bf16 v[126:129], v[154:157], v[170:173], v[126:129]
	v_mfma_f32_16x16x32_bf16 v[122:125], v[162:165], v[170:173], v[122:125]
	v_mfma_f32_16x16x32_bf16 v[118:121], v[154:157], v[182:185], v[118:121]
	v_mfma_f32_16x16x32_bf16 v[114:117], v[162:165], v[182:185], v[114:117]
	v_mfma_f32_16x16x32_bf16 v[110:113], v[150:153], v[196:199], v[110:113]
	v_mfma_f32_16x16x32_bf16 v[106:109], v[158:161], v[196:199], v[106:109]
	s_waitcnt lgkmcnt(0)
	v_mfma_f32_16x16x32_bf16 v[102:105], v[154:157], v[208:211], v[102:105]
	v_mfma_f32_16x16x32_bf16 v[98:101], v[162:165], v[208:211], v[98:101]
	v_mfma_f32_16x16x32_bf16 v[214:217], v[154:157], v[200:203], v[110:113]
	v_mfma_f32_16x16x32_bf16 v[218:221], v[162:165], v[200:203], v[106:109]
	s_setprio 0
	v_add3_u32 v175, s77, v176, v149
	s_barrier
	ds_read_b128 v[106:109], v175
	ds_read_b128 v[110:113], v175 offset:1024
	ds_read_b128 v[222:225], v175 offset:2048
	ds_read_b128 v[226:229], v175 offset:3072
	s_barrier
	s_waitcnt lgkmcnt(0)
	s_setprio 1
	s_waitcnt lgkmcnt(3)
	v_mfma_f32_16x16x32_bf16 v[94:97], v[106:109], v[166:169], v[94:97]
	s_waitcnt lgkmcnt(1)
	v_mfma_f32_16x16x32_bf16 v[82:85], v[222:225], v[178:181], v[82:85]
	v_mfma_f32_16x16x32_bf16 v[78:81], v[106:109], v[196:199], v[78:81]
	v_mfma_f32_16x16x32_bf16 v[74:77], v[222:225], v[196:199], v[74:77]
	v_mfma_f32_16x16x32_bf16 v[70:73], v[106:109], v[204:207], v[70:73]
	v_mfma_f32_16x16x32_bf16 v[66:69], v[222:225], v[204:207], v[66:69]
	v_mfma_f32_16x16x32_bf16 v[94:97], v[110:113], v[170:173], v[94:97]
	v_mfma_f32_16x16x32_bf16 v[90:93], v[222:225], v[166:169], v[90:93]
	v_mfma_f32_16x16x32_bf16 v[86:89], v[106:109], v[178:181], v[86:89]
	s_waitcnt lgkmcnt(0)
	v_mfma_f32_16x16x32_bf16 v[82:85], v[226:229], v[182:185], v[82:85]
	v_mfma_f32_16x16x32_bf16 v[78:81], v[110:113], v[200:203], v[78:81]
	v_mfma_f32_16x16x32_bf16 v[74:77], v[226:229], v[200:203], v[74:77]
	v_mfma_f32_16x16x32_bf16 v[70:73], v[110:113], v[208:211], v[70:73]
	v_mfma_f32_16x16x32_bf16 v[66:69], v[226:229], v[208:211], v[66:69]
	v_mfma_f32_16x16x32_bf16 v[166:169], v[226:229], v[170:173], v[90:93]
	v_mfma_f32_16x16x32_bf16 v[170:173], v[110:113], v[182:185], v[86:89]
	s_setprio 0
	s_barrier
	s_nop 0
	ds_read_b128 v[86:89], v190 offset:16384
	ds_read_b128 v[90:93], v190 offset:17408
	ds_read_b128 v[178:181], v174 offset:18432
	ds_read_b128 v[182:185], v174 offset:19456
	ds_read_b128 v[196:199], v174 offset:20480
	ds_read_b128 v[200:203], v174 offset:21504
	ds_read_b128 v[204:207], v174 offset:22528
	ds_read_b128 v[208:211], v174 offset:23552
	s_waitcnt vmcnt(4)
	s_barrier
	s_waitcnt lgkmcnt(0)
	s_setprio 1
	s_waitcnt lgkmcnt(5)
	v_mfma_f32_16x16x32_bf16 v[54:57], v[150:153], v[178:181], v[54:57]
	v_mfma_f32_16x16x32_bf16 v[50:53], v[158:161], v[178:181], v[50:53]
	v_mfma_f32_16x16x32_bf16 v[62:65], v[150:153], v[86:89], v[62:65]
	v_mfma_f32_16x16x32_bf16 v[58:61], v[158:161], v[86:89], v[58:61]
	s_waitcnt lgkmcnt(4)
	v_mfma_f32_16x16x32_bf16 v[54:57], v[154:157], v[182:185], v[54:57]
	v_mfma_f32_16x16x32_bf16 v[50:53], v[162:165], v[182:185], v[50:53]
	s_waitcnt lgkmcnt(3)
	v_mfma_f32_16x16x32_bf16 v[46:49], v[150:153], v[196:199], v[46:49]
	v_mfma_f32_16x16x32_bf16 v[42:45], v[158:161], v[196:199], v[42:45]
	s_waitcnt lgkmcnt(1)
	v_mfma_f32_16x16x32_bf16 v[38:41], v[150:153], v[204:207], v[38:41]
	v_mfma_f32_16x16x32_bf16 v[34:37], v[158:161], v[204:207], v[34:37]
	v_mfma_f32_16x16x32_bf16 v[230:233], v[154:157], v[90:93], v[62:65]
	v_mfma_f32_16x16x32_bf16 v[234:237], v[162:165], v[90:93], v[58:61]
	v_mfma_f32_16x16x32_bf16 v[238:241], v[154:157], v[200:203], v[46:49]
	v_mfma_f32_16x16x32_bf16 v[242:245], v[162:165], v[200:203], v[42:45]
	s_waitcnt lgkmcnt(0)
	v_mfma_f32_16x16x32_bf16 v[150:153], v[154:157], v[208:211], v[38:41]
	v_mfma_f32_16x16x32_bf16 v[154:157], v[162:165], v[208:211], v[34:37]
	s_setprio 0
	s_setprio 1
	v_mfma_f32_16x16x32_bf16 v[30:33], v[106:109], v[86:89], v[30:33]
	v_mfma_f32_16x16x32_bf16 v[26:29], v[222:225], v[86:89], v[26:29]
	v_mfma_f32_16x16x32_bf16 v[12:15], v[106:109], v[196:199], v[12:15]
	v_mfma_f32_16x16x32_bf16 v[8:11], v[222:225], v[196:199], v[8:11]
	v_mfma_f32_16x16x32_bf16 v[30:33], v[110:113], v[90:93], v[30:33]
	v_mfma_f32_16x16x32_bf16 v[26:29], v[226:229], v[90:93], v[26:29]
	v_mfma_f32_16x16x32_bf16 v[22:25], v[106:109], v[178:181], v[22:25]
	v_mfma_f32_16x16x32_bf16 v[18:21], v[222:225], v[178:181], v[18:21]
	v_mfma_f32_16x16x32_bf16 v[12:15], v[110:113], v[200:203], v[12:15]
	v_mfma_f32_16x16x32_bf16 v[8:11], v[226:229], v[200:203], v[8:11]
	v_mfma_f32_16x16x32_bf16 v[4:7], v[106:109], v[204:207], v[4:7]
	v_mfma_f32_16x16x32_bf16 v[0:3], v[222:225], v[204:207], v[0:3]
	v_mfma_f32_16x16x32_bf16 v[158:161], v[110:113], v[182:185], v[22:25]
	v_mfma_f32_16x16x32_bf16 v[162:165], v[226:229], v[182:185], v[18:21]
	v_mfma_f32_16x16x32_bf16 v[178:181], v[110:113], v[208:211], v[4:7]
	v_mfma_f32_16x16x32_bf16 v[182:185], v[226:229], v[208:211], v[0:3]
	s_setprio 0
	v_add3_u32 v18, s2, v176, v149
	s_barrier
	s_nop 0
	ds_read_b128 v[0:3], v18
	ds_read_b128 v[4:7], v18 offset:1024
	ds_read_b128 v[196:199], v18 offset:2048
	ds_read_b128 v[200:203], v18 offset:3072
	ds_read_b128 v[18:21], v190 offset:32768
	ds_read_b128 v[22:25], v190 offset:33792
	ds_read_b128 v[42:45], v174 offset:34816
	ds_read_b128 v[46:49], v174 offset:35840
	ds_read_b128 v[204:207], v174 offset:36864
	ds_read_b128 v[208:211], v174 offset:37888
	ds_read_b128 v[222:225], v174 offset:38912
	ds_read_b128 v[226:229], v174 offset:39936
	s_waitcnt vmcnt(2)
	s_barrier
	s_waitcnt lgkmcnt(0)
	s_setprio 1
	s_waitcnt lgkmcnt(7)
	v_mfma_f32_16x16x32_bf16 v[34:37], v[0:3], v[18:21], v[126:129]
	s_waitcnt lgkmcnt(6)
	v_mfma_f32_16x16x32_bf16 v[110:113], v[4:7], v[22:25], v[34:37]
	v_mfma_f32_16x16x32_bf16 v[34:37], v[196:199], v[18:21], v[122:125]
	v_mfma_f32_16x16x32_bf16 v[106:109], v[200:203], v[22:25], v[34:37]
	s_waitcnt lgkmcnt(5)
	v_mfma_f32_16x16x32_bf16 v[34:37], v[0:3], v[42:45], v[118:121]
	s_waitcnt lgkmcnt(4)
	v_mfma_f32_16x16x32_bf16 v[90:93], v[4:7], v[46:49], v[34:37]
	v_mfma_f32_16x16x32_bf16 v[34:37], v[196:199], v[42:45], v[114:117]
	v_mfma_f32_16x16x32_bf16 v[86:89], v[200:203], v[46:49], v[34:37]
	s_waitcnt lgkmcnt(3)
	v_mfma_f32_16x16x32_bf16 v[34:37], v[0:3], v[204:207], v[214:217]
	s_waitcnt lgkmcnt(2)
	v_mfma_f32_16x16x32_bf16 v[62:65], v[4:7], v[208:211], v[34:37]
	v_mfma_f32_16x16x32_bf16 v[34:37], v[196:199], v[204:207], v[218:221]
	v_mfma_f32_16x16x32_bf16 v[58:61], v[200:203], v[208:211], v[34:37]
	s_waitcnt lgkmcnt(1)
	v_mfma_f32_16x16x32_bf16 v[34:37], v[0:3], v[222:225], v[102:105]
	s_waitcnt lgkmcnt(0)
	v_mfma_f32_16x16x32_bf16 v[38:41], v[4:7], v[226:229], v[34:37]
	v_mfma_f32_16x16x32_bf16 v[34:37], v[196:199], v[222:225], v[98:101]
	v_mfma_f32_16x16x32_bf16 v[34:37], v[200:203], v[226:229], v[34:37]
	s_setprio 0
	s_nop 0
	v_add3_u32 v98, s91, v176, v149
	s_barrier
	ds_read_b128 v[214:217], v98
	ds_read_b128 v[218:221], v98 offset:1024
	ds_read_b128 v[246:249], v98 offset:2048
	ds_read_b128 v[250:253], v98 offset:3072
	s_waitcnt vmcnt(0)
	s_barrier
	s_waitcnt lgkmcnt(0)
	s_setprio 1
	s_waitcnt lgkmcnt(3)
	v_mfma_f32_16x16x32_bf16 v[94:97], v[214:217], v[18:21], v[94:97]
	s_waitcnt lgkmcnt(1)
	v_mfma_f32_16x16x32_bf16 v[18:21], v[246:249], v[18:21], v[166:169]
	s_waitcnt lgkmcnt(0)
	v_mfma_f32_16x16x32_bf16 v[122:125], v[250:253], v[22:25], v[18:21]
	v_mfma_f32_16x16x32_bf16 v[18:21], v[214:217], v[42:45], v[170:173]
	v_mfma_f32_16x16x32_bf16 v[118:121], v[218:221], v[46:49], v[18:21]
	v_mfma_f32_16x16x32_bf16 v[18:21], v[246:249], v[42:45], v[82:85]
	v_mfma_f32_16x16x32_bf16 v[114:117], v[250:253], v[46:49], v[18:21]
	v_mfma_f32_16x16x32_bf16 v[18:21], v[214:217], v[204:207], v[78:81]
	v_mfma_f32_16x16x32_bf16 v[102:105], v[218:221], v[208:211], v[18:21]
	v_mfma_f32_16x16x32_bf16 v[18:21], v[246:249], v[204:207], v[74:77]
	v_mfma_f32_16x16x32_bf16 v[126:129], v[218:221], v[22:25], v[94:97]
	v_mfma_f32_16x16x32_bf16 v[94:97], v[250:253], v[208:211], v[18:21]
	v_mfma_f32_16x16x32_bf16 v[18:21], v[214:217], v[222:225], v[70:73]
	v_mfma_f32_16x16x32_bf16 v[70:73], v[218:221], v[226:229], v[18:21]
	v_mfma_f32_16x16x32_bf16 v[18:21], v[246:249], v[222:225], v[66:69]
	v_mfma_f32_16x16x32_bf16 v[66:69], v[250:253], v[226:229], v[18:21]
	s_setprio 0
	s_barrier
	ds_read_b128 v[82:85], v190 offset:49152
	ds_read_b128 v[166:169], v190 offset:50176
	ds_read_b128 v[170:173], v174 offset:51200
	ds_read_b128 v[204:207], v174 offset:52224
	ds_read_b128 v[208:211], v174 offset:53248
	ds_read_b128 v[222:225], v174 offset:54272
	ds_read_b128 v[226:229], v174 offset:55296
	ds_read_b128 v[174:177], v174 offset:56320
	s_barrier
	s_waitcnt lgkmcnt(0)
	s_setprio 1
	s_waitcnt lgkmcnt(7)
	v_mfma_f32_16x16x32_bf16 v[18:21], v[0:3], v[82:85], v[230:233]
	s_waitcnt lgkmcnt(6)
	v_mfma_f32_16x16x32_bf16 v[78:81], v[4:7], v[166:169], v[18:21]
	v_mfma_f32_16x16x32_bf16 v[18:21], v[196:199], v[82:85], v[234:237]
	v_mfma_f32_16x16x32_bf16 v[74:77], v[200:203], v[166:169], v[18:21]
	s_waitcnt lgkmcnt(5)
	v_mfma_f32_16x16x32_bf16 v[18:21], v[0:3], v[170:173], v[54:57]
	s_waitcnt lgkmcnt(4)
	v_mfma_f32_16x16x32_bf16 v[46:49], v[4:7], v[204:207], v[18:21]
	v_mfma_f32_16x16x32_bf16 v[18:21], v[196:199], v[170:173], v[50:53]
	v_mfma_f32_16x16x32_bf16 v[42:45], v[200:203], v[204:207], v[18:21]
	s_waitcnt lgkmcnt(3)
	v_mfma_f32_16x16x32_bf16 v[18:21], v[0:3], v[208:211], v[238:241]
	s_waitcnt lgkmcnt(1)
	v_mfma_f32_16x16x32_bf16 v[0:3], v[0:3], v[226:229], v[150:153]
	v_mfma_f32_16x16x32_bf16 v[22:25], v[4:7], v[222:225], v[18:21]
	v_mfma_f32_16x16x32_bf16 v[18:21], v[196:199], v[208:211], v[242:245]
	s_waitcnt lgkmcnt(0)
	v_mfma_f32_16x16x32_bf16 v[4:7], v[4:7], v[174:177], v[0:3]
	v_mfma_f32_16x16x32_bf16 v[0:3], v[196:199], v[226:229], v[154:157]
	v_mfma_f32_16x16x32_bf16 v[18:21], v[200:203], v[222:225], v[18:21]
	v_mfma_f32_16x16x32_bf16 v[0:3], v[200:203], v[174:177], v[0:3]
	s_setprio 0
	s_setprio 1
	v_mfma_f32_16x16x32_bf16 v[26:29], v[246:249], v[82:85], v[26:29]
	v_mfma_f32_16x16x32_bf16 v[30:33], v[214:217], v[82:85], v[30:33]
	v_mfma_f32_16x16x32_bf16 v[82:85], v[250:253], v[166:169], v[26:29]
	v_mfma_f32_16x16x32_bf16 v[26:29], v[214:217], v[170:173], v[158:161]
	v_mfma_f32_16x16x32_bf16 v[54:57], v[218:221], v[204:207], v[26:29]
	v_mfma_f32_16x16x32_bf16 v[26:29], v[246:249], v[170:173], v[162:165]
	v_mfma_f32_16x16x32_bf16 v[8:11], v[246:249], v[208:211], v[8:11]
	v_mfma_f32_16x16x32_bf16 v[50:53], v[250:253], v[204:207], v[26:29]
	v_mfma_f32_16x16x32_bf16 v[12:15], v[214:217], v[208:211], v[12:15]
	v_mfma_f32_16x16x32_bf16 v[26:29], v[250:253], v[222:225], v[8:11]
	v_mfma_f32_16x16x32_bf16 v[8:11], v[214:217], v[226:229], v[178:181]
	v_mfma_f32_16x16x32_bf16 v[98:101], v[218:221], v[166:169], v[30:33]
	v_mfma_f32_16x16x32_bf16 v[30:33], v[218:221], v[222:225], v[12:15]
	v_mfma_f32_16x16x32_bf16 v[12:15], v[218:221], v[174:177], v[8:11]
	v_mfma_f32_16x16x32_bf16 v[8:11], v[246:249], v[226:229], v[182:185]
	v_mfma_f32_16x16x32_bf16 v[8:11], v[250:253], v[174:177], v[8:11]
	s_setprio 0
	s_movk_i32 s1, 0x100
	s_nop 0
	v_cmp_gt_u32_e32 vcc, s1, v144
	s_barrier
	s_and_saveexec_b64 s[6:7], vcc
	s_cbranch_execz .LBB0_529
	s_barrier

.LBB0_530:
	v_or_b32_e32 v38, s10, v1
	v_mad_u64_u32 v[34:35], s[10:11], v38, s43, v[0:1]
	ds_read_b128 v[4:7], v34
	ds_read_b128 v[8:11], v34 offset:1056
	v_ashrrev_i32_e32 v39, 31, v38
	v_or_b32_e32 v40, 2, v38
	v_or_b32_e32 v42, 4, v38
	v_or_b32_e32 v44, 6, v38
	v_or_b32_e32 v46, 8, v38
	v_or_b32_e32 v48, 10, v38
	v_or_b32_e32 v50, 12, v38
	v_or_b32_e32 v52, 14, v38
	v_lshlrev_b64 v[38:39], 12, v[38:39]
	ds_read_b128 v[12:15], v34 offset:2112
	ds_read_b128 v[18:21], v34 offset:3168
	v_lshl_add_u64 v[38:39], v[2:3], 0, v[38:39]
	v_ashrrev_i32_e32 v41, 31, v40
	s_waitcnt lgkmcnt(3)
	global_store_dwordx4 v[38:39], v[4:7], off nt
	v_ashrrev_i32_e32 v43, 31, v42
	ds_read_b128 v[22:25], v34 offset:4224
	ds_read_b128 v[26:29], v34 offset:5280
	v_lshlrev_b64 v[4:5], 12, v[40:41]
	v_lshl_add_u64 v[4:5], v[2:3], 0, v[4:5]
	s_waitcnt lgkmcnt(4)
	global_store_dwordx4 v[4:5], v[8:11], off nt
	v_lshlrev_b64 v[4:5], 12, v[42:43]
	v_lshl_add_u64 v[4:5], v[2:3], 0, v[4:5]
	v_ashrrev_i32_e32 v45, 31, v44
	s_waitcnt lgkmcnt(3)
	global_store_dwordx4 v[4:5], v[12:15], off nt
	v_lshlrev_b64 v[4:5], 12, v[44:45]
	v_lshl_add_u64 v[4:5], v[2:3], 0, v[4:5]
	v_ashrrev_i32_e32 v47, 31, v46
	s_waitcnt lgkmcnt(2)
	global_store_dwordx4 v[4:5], v[18:21], off nt
	v_lshlrev_b64 v[4:5], 12, v[46:47]
	ds_read_b128 v[30:33], v34 offset:6336
	v_lshl_add_u64 v[4:5], v[2:3], 0, v[4:5]
	v_ashrrev_i32_e32 v49, 31, v48
	s_waitcnt lgkmcnt(2)
	global_store_dwordx4 v[4:5], v[22:25], off nt
	v_lshlrev_b64 v[4:5], 12, v[48:49]
	ds_read_b128 v[34:37], v34 offset:7392
	v_lshl_add_u64 v[4:5], v[2:3], 0, v[4:5]
	v_ashrrev_i32_e32 v51, 31, v50
	s_waitcnt lgkmcnt(2)
	global_store_dwordx4 v[4:5], v[26:29], off nt
	v_lshlrev_b64 v[4:5], 12, v[50:51]
	v_lshl_add_u64 v[4:5], v[2:3], 0, v[4:5]
	v_ashrrev_i32_e32 v53, 31, v52
	s_waitcnt lgkmcnt(1)
	global_store_dwordx4 v[4:5], v[30:33], off nt
	v_lshlrev_b64 v[4:5], 12, v[52:53]
	v_lshl_add_u64 v[4:5], v[2:3], 0, v[4:5]
	s_mov_b32 s10, 16
	s_and_b64 vcc, exec, s[6:7]
	s_mov_b64 s[6:7], 0
	s_waitcnt lgkmcnt(0)
	global_store_dwordx4 v[4:5], v[34:37], off nt
	s_cbranch_vccnz .LBB0_530
	s_add_i32 s14, s14, 1
	s_mov_b64 s[10:11], 0
	s_barrier
	s_barrier
	s_branch .LBB0_517
	s_nop 0

.LBB0_646:
	ds_read_b128 v[144:147], v136
	ds_read_b128 v[148:151], v136 offset:1024
	ds_read_b128 v[152:155], v136 offset:2048
	ds_read_b128 v[156:159], v136 offset:3072
	s_add_i32 s39, s19, s38
	s_add_i32 s61, s39, 0x80080
	s_mov_b32 m0, s13
	ds_read_b128 v[160:163], v137
	ds_read_b128 v[164:167], v137 offset:1024
	ds_read_b128 v[168:171], v138
	ds_read_b128 v[172:175], v138 offset:1024
	ds_read_b128 v[176:179], v139
	ds_read_b128 v[180:183], v139 offset:1024
	ds_read_b128 v[196:199], v140
	ds_read_b128 v[200:203], v140 offset:1024
	buffer_load_dwordx4 v134, s[48:51], s61 offen lds
	s_mov_b32 m0, s12
	s_nop 0
	buffer_load_dwordx4 v135, s[48:51], s61 offen lds
	s_waitcnt lgkmcnt(8)
	s_barrier
	s_waitcnt lgkmcnt(0)
	s_setprio 1
	s_waitcnt lgkmcnt(0)
	v_mfma_f32_16x16x32_bf16 v[126:129], v[144:147], v[160:163], v[126:129]
	v_mfma_f32_16x16x32_bf16 v[122:125], v[152:155], v[160:163], v[122:125]
	v_mfma_f32_16x16x32_bf16 v[118:121], v[144:147], v[168:171], v[118:121]
	v_mfma_f32_16x16x32_bf16 v[114:117], v[152:155], v[168:171], v[114:117]
	v_mfma_f32_16x16x32_bf16 v[110:113], v[144:147], v[176:179], v[110:113]
	v_mfma_f32_16x16x32_bf16 v[106:109], v[152:155], v[176:179], v[106:109]
	v_mfma_f32_16x16x32_bf16 v[102:105], v[144:147], v[196:199], v[102:105]
	v_mfma_f32_16x16x32_bf16 v[98:101], v[152:155], v[196:199], v[98:101]
	v_mfma_f32_16x16x32_bf16 v[126:129], v[148:151], v[164:167], v[126:129]
	v_mfma_f32_16x16x32_bf16 v[122:125], v[156:159], v[164:167], v[122:125]
	v_mfma_f32_16x16x32_bf16 v[118:121], v[148:151], v[172:175], v[118:121]
	v_mfma_f32_16x16x32_bf16 v[114:117], v[156:159], v[172:175], v[114:117]
	v_mfma_f32_16x16x32_bf16 v[110:113], v[148:151], v[180:183], v[110:113]
	v_mfma_f32_16x16x32_bf16 v[106:109], v[156:159], v[180:183], v[106:109]
	v_mfma_f32_16x16x32_bf16 v[102:105], v[148:151], v[200:203], v[102:105]
	v_mfma_f32_16x16x32_bf16 v[98:101], v[156:159], v[200:203], v[98:101]
	s_setprio 0
	s_barrier
	s_add_i32 s61, s20, s38
	s_add_i32 s62, s61, 0x100
	s_mov_b32 m0, s22
	ds_read_b128 v[204:207], v141
	ds_read_b128 v[208:211], v141 offset:1024
	ds_read_b128 v[214:217], v141 offset:2048
	ds_read_b128 v[218:221], v141 offset:3072
	buffer_load_dwordx4 v134, s[52:55], s62 offen lds
	s_mov_b32 m0, s23
	s_nop 0
	buffer_load_dwordx4 v135, s[52:55], s62 offen lds
	s_barrier
	s_waitcnt lgkmcnt(0)
	s_setprio 1
	s_waitcnt lgkmcnt(0)
	v_mfma_f32_16x16x32_bf16 v[94:97], v[204:207], v[160:163], v[94:97]
	v_mfma_f32_16x16x32_bf16 v[90:93], v[214:217], v[160:163], v[90:93]
	v_mfma_f32_16x16x32_bf16 v[86:89], v[204:207], v[168:171], v[86:89]
	v_mfma_f32_16x16x32_bf16 v[82:85], v[214:217], v[168:171], v[82:85]
	v_mfma_f32_16x16x32_bf16 v[78:81], v[204:207], v[176:179], v[78:81]
	v_mfma_f32_16x16x32_bf16 v[74:77], v[214:217], v[176:179], v[74:77]
	v_mfma_f32_16x16x32_bf16 v[70:73], v[204:207], v[196:199], v[70:73]
	v_mfma_f32_16x16x32_bf16 v[66:69], v[214:217], v[196:199], v[66:69]
	v_mfma_f32_16x16x32_bf16 v[94:97], v[208:211], v[164:167], v[94:97]
	v_mfma_f32_16x16x32_bf16 v[90:93], v[218:221], v[164:167], v[90:93]
	v_mfma_f32_16x16x32_bf16 v[86:89], v[208:211], v[172:175], v[86:89]
	v_mfma_f32_16x16x32_bf16 v[82:85], v[218:221], v[172:175], v[82:85]
	v_mfma_f32_16x16x32_bf16 v[78:81], v[208:211], v[180:183], v[78:81]
	v_mfma_f32_16x16x32_bf16 v[74:77], v[218:221], v[180:183], v[74:77]
	v_mfma_f32_16x16x32_bf16 v[70:73], v[208:211], v[200:203], v[70:73]
	v_mfma_f32_16x16x32_bf16 v[66:69], v[218:221], v[200:203], v[66:69]
	s_setprio 0
	s_add_i32 s62, s39, 0x100
	s_mov_b32 m0, s21
	s_barrier
	ds_read_b128 v[160:163], v137 offset:16384
	ds_read_b128 v[164:167], v137 offset:17408
	ds_read_b128 v[168:171], v138 offset:16384
	ds_read_b128 v[172:175], v138 offset:17408
	ds_read_b128 v[176:179], v139 offset:16384
	ds_read_b128 v[180:183], v139 offset:17408
	ds_read_b128 v[196:199], v140 offset:16384
	ds_read_b128 v[200:203], v140 offset:17408
	buffer_load_dwordx4 v134, s[48:51], s62 offen lds
	s_mov_b32 m0, s24
	s_nop 0
	buffer_load_dwordx4 v135, s[48:51], s62 offen lds
	s_barrier
	s_waitcnt lgkmcnt(0)
	s_setprio 1
	s_waitcnt lgkmcnt(0)
	v_mfma_f32_16x16x32_bf16 v[62:65], v[144:147], v[160:163], v[62:65]
	v_mfma_f32_16x16x32_bf16 v[58:61], v[152:155], v[160:163], v[58:61]
	v_mfma_f32_16x16x32_bf16 v[54:57], v[144:147], v[168:171], v[54:57]
	v_mfma_f32_16x16x32_bf16 v[50:53], v[152:155], v[168:171], v[50:53]
	v_mfma_f32_16x16x32_bf16 v[46:49], v[144:147], v[176:179], v[46:49]
	v_mfma_f32_16x16x32_bf16 v[42:45], v[152:155], v[176:179], v[42:45]
	v_mfma_f32_16x16x32_bf16 v[38:41], v[144:147], v[196:199], v[38:41]
	v_mfma_f32_16x16x32_bf16 v[34:37], v[152:155], v[196:199], v[34:37]
	v_mfma_f32_16x16x32_bf16 v[62:65], v[148:151], v[164:167], v[62:65]
	v_mfma_f32_16x16x32_bf16 v[58:61], v[156:159], v[164:167], v[58:61]
	v_mfma_f32_16x16x32_bf16 v[54:57], v[148:151], v[172:175], v[54:57]
	v_mfma_f32_16x16x32_bf16 v[50:53], v[156:159], v[172:175], v[50:53]
	v_mfma_f32_16x16x32_bf16 v[46:49], v[148:151], v[180:183], v[46:49]
	v_mfma_f32_16x16x32_bf16 v[42:45], v[156:159], v[180:183], v[42:45]
	v_mfma_f32_16x16x32_bf16 v[38:41], v[148:151], v[200:203], v[38:41]
	v_mfma_f32_16x16x32_bf16 v[34:37], v[156:159], v[200:203], v[34:37]
	s_setprio 0
	s_barrier
	s_add_i32 s62, s61, 0x80100
	s_mov_b32 m0, s25
	s_nop 0
	buffer_load_dwordx4 v134, s[52:55], s62 offen lds
	s_mov_b32 m0, s26
	s_nop 0
	buffer_load_dwordx4 v135, s[52:55], s62 offen lds
	s_waitcnt vmcnt(6)
	s_barrier
	s_setprio 1
	v_mfma_f32_16x16x32_bf16 v[30:33], v[204:207], v[160:163], v[30:33]
	v_mfma_f32_16x16x32_bf16 v[26:29], v[214:217], v[160:163], v[26:29]
	v_mfma_f32_16x16x32_bf16 v[22:25], v[204:207], v[168:171], v[22:25]
	v_mfma_f32_16x16x32_bf16 v[18:21], v[214:217], v[168:171], v[18:21]
	v_mfma_f32_16x16x32_bf16 v[12:15], v[204:207], v[176:179], v[12:15]
	v_mfma_f32_16x16x32_bf16 v[8:11], v[214:217], v[176:179], v[8:11]
	v_mfma_f32_16x16x32_bf16 v[4:7], v[204:207], v[196:199], v[4:7]
	v_mfma_f32_16x16x32_bf16 v[0:3], v[214:217], v[196:199], v[0:3]
	v_mfma_f32_16x16x32_bf16 v[30:33], v[208:211], v[164:167], v[30:33]
	v_mfma_f32_16x16x32_bf16 v[26:29], v[218:221], v[164:167], v[26:29]
	v_mfma_f32_16x16x32_bf16 v[22:25], v[208:211], v[172:175], v[22:25]
	v_mfma_f32_16x16x32_bf16 v[18:21], v[218:221], v[172:175], v[18:21]
	v_mfma_f32_16x16x32_bf16 v[12:15], v[208:211], v[180:183], v[12:15]
	v_mfma_f32_16x16x32_bf16 v[8:11], v[218:221], v[180:183], v[8:11]
	v_mfma_f32_16x16x32_bf16 v[4:7], v[208:211], v[200:203], v[4:7]
	v_mfma_f32_16x16x32_bf16 v[0:3], v[218:221], v[200:203], v[0:3]
	s_setprio 0
	s_barrier
	ds_read_b128 v[144:147], v142
	ds_read_b128 v[148:151], v142 offset:1024
	ds_read_b128 v[152:155], v142 offset:2048
	ds_read_b128 v[156:159], v142 offset:3072
	s_add_i32 s62, s39, 0x80100
	s_mov_b32 m0, s27
	ds_read_b128 v[160:163], v137 offset:32768
	ds_read_b128 v[164:167], v137 offset:33792
	ds_read_b128 v[168:171], v138 offset:32768
	ds_read_b128 v[172:175], v138 offset:33792
	ds_read_b128 v[176:179], v139 offset:32768
	ds_read_b128 v[180:183], v139 offset:33792
	ds_read_b128 v[196:199], v140 offset:32768
	ds_read_b128 v[200:203], v140 offset:33792
	buffer_load_dwordx4 v134, s[48:51], s62 offen lds
	s_mov_b32 m0, s28
	s_nop 0
	buffer_load_dwordx4 v135, s[48:51], s62 offen lds
	s_waitcnt lgkmcnt(8)
	s_barrier
	s_waitcnt lgkmcnt(0)
	s_setprio 1
	s_waitcnt lgkmcnt(0)
	v_mfma_f32_16x16x32_bf16 v[126:129], v[144:147], v[160:163], v[126:129]
	v_mfma_f32_16x16x32_bf16 v[122:125], v[152:155], v[160:163], v[122:125]
	v_mfma_f32_16x16x32_bf16 v[118:121], v[144:147], v[168:171], v[118:121]
	v_mfma_f32_16x16x32_bf16 v[114:117], v[152:155], v[168:171], v[114:117]
	v_mfma_f32_16x16x32_bf16 v[110:113], v[144:147], v[176:179], v[110:113]
	v_mfma_f32_16x16x32_bf16 v[106:109], v[152:155], v[176:179], v[106:109]
	v_mfma_f32_16x16x32_bf16 v[102:105], v[144:147], v[196:199], v[102:105]
	v_mfma_f32_16x16x32_bf16 v[98:101], v[152:155], v[196:199], v[98:101]
	v_mfma_f32_16x16x32_bf16 v[126:129], v[148:151], v[164:167], v[126:129]
	v_mfma_f32_16x16x32_bf16 v[122:125], v[156:159], v[164:167], v[122:125]
	v_mfma_f32_16x16x32_bf16 v[118:121], v[148:151], v[172:175], v[118:121]
	v_mfma_f32_16x16x32_bf16 v[114:117], v[156:159], v[172:175], v[114:117]
	v_mfma_f32_16x16x32_bf16 v[110:113], v[148:151], v[180:183], v[110:113]
	v_mfma_f32_16x16x32_bf16 v[106:109], v[156:159], v[180:183], v[106:109]
	v_mfma_f32_16x16x32_bf16 v[102:105], v[148:151], v[200:203], v[102:105]
	v_mfma_f32_16x16x32_bf16 v[98:101], v[156:159], v[200:203], v[98:101]
	s_setprio 0
	s_barrier
	s_add_i32 s62, s61, 0x180
	s_mov_b32 m0, s29
	ds_read_b128 v[204:207], v143
	ds_read_b128 v[208:211], v143 offset:1024
	ds_read_b128 v[214:217], v143 offset:2048
	ds_read_b128 v[218:221], v143 offset:3072
	buffer_load_dwordx4 v134, s[52:55], s62 offen lds
	s_mov_b32 m0, s30
	s_nop 0
	buffer_load_dwordx4 v135, s[52:55], s62 offen lds
	s_barrier
	s_waitcnt lgkmcnt(0)
	s_setprio 1
	s_waitcnt lgkmcnt(0)
	v_mfma_f32_16x16x32_bf16 v[94:97], v[204:207], v[160:163], v[94:97]
	v_mfma_f32_16x16x32_bf16 v[90:93], v[214:217], v[160:163], v[90:93]
	v_mfma_f32_16x16x32_bf16 v[86:89], v[204:207], v[168:171], v[86:89]
	v_mfma_f32_16x16x32_bf16 v[82:85], v[214:217], v[168:171], v[82:85]
	v_mfma_f32_16x16x32_bf16 v[78:81], v[204:207], v[176:179], v[78:81]
	v_mfma_f32_16x16x32_bf16 v[74:77], v[214:217], v[176:179], v[74:77]
	v_mfma_f32_16x16x32_bf16 v[70:73], v[204:207], v[196:199], v[70:73]
	v_mfma_f32_16x16x32_bf16 v[66:69], v[214:217], v[196:199], v[66:69]
	v_mfma_f32_16x16x32_bf16 v[94:97], v[208:211], v[164:167], v[94:97]
	v_mfma_f32_16x16x32_bf16 v[90:93], v[218:221], v[164:167], v[90:93]
	v_mfma_f32_16x16x32_bf16 v[86:89], v[208:211], v[172:175], v[86:89]
	v_mfma_f32_16x16x32_bf16 v[82:85], v[218:221], v[172:175], v[82:85]
	v_mfma_f32_16x16x32_bf16 v[78:81], v[208:211], v[180:183], v[78:81]
	v_mfma_f32_16x16x32_bf16 v[74:77], v[218:221], v[180:183], v[74:77]
	v_mfma_f32_16x16x32_bf16 v[70:73], v[208:211], v[200:203], v[70:73]
	v_mfma_f32_16x16x32_bf16 v[66:69], v[218:221], v[200:203], v[66:69]
	s_setprio 0
	s_addk_i32 s39, 0x180
	s_mov_b32 m0, s31
	s_barrier
	ds_read_b128 v[160:163], v137 offset:49152
	ds_read_b128 v[164:167], v137 offset:50176
	ds_read_b128 v[168:171], v138 offset:49152
	ds_read_b128 v[172:175], v138 offset:50176
	ds_read_b128 v[176:179], v139 offset:49152
	ds_read_b128 v[180:183], v139 offset:50176
	ds_read_b128 v[196:199], v140 offset:49152
	ds_read_b128 v[200:203], v140 offset:50176
	buffer_load_dwordx4 v134, s[48:51], s39 offen lds
	s_mov_b32 m0, s34
	s_nop 0
	buffer_load_dwordx4 v135, s[48:51], s39 offen lds
	s_barrier
	s_waitcnt lgkmcnt(0)
	s_setprio 1
	s_waitcnt lgkmcnt(0)
	v_mfma_f32_16x16x32_bf16 v[62:65], v[144:147], v[160:163], v[62:65]
	v_mfma_f32_16x16x32_bf16 v[58:61], v[152:155], v[160:163], v[58:61]
	v_mfma_f32_16x16x32_bf16 v[54:57], v[144:147], v[168:171], v[54:57]
	v_mfma_f32_16x16x32_bf16 v[50:53], v[152:155], v[168:171], v[50:53]
	v_mfma_f32_16x16x32_bf16 v[46:49], v[144:147], v[176:179], v[46:49]
	v_mfma_f32_16x16x32_bf16 v[42:45], v[152:155], v[176:179], v[42:45]
	v_mfma_f32_16x16x32_bf16 v[38:41], v[144:147], v[196:199], v[38:41]
	v_mfma_f32_16x16x32_bf16 v[34:37], v[152:155], v[196:199], v[34:37]
	v_mfma_f32_16x16x32_bf16 v[62:65], v[148:151], v[164:167], v[62:65]
	v_mfma_f32_16x16x32_bf16 v[58:61], v[156:159], v[164:167], v[58:61]
	v_mfma_f32_16x16x32_bf16 v[54:57], v[148:151], v[172:175], v[54:57]
	v_mfma_f32_16x16x32_bf16 v[50:53], v[156:159], v[172:175], v[50:53]
	v_mfma_f32_16x16x32_bf16 v[46:49], v[148:151], v[180:183], v[46:49]
	v_mfma_f32_16x16x32_bf16 v[42:45], v[156:159], v[180:183], v[42:45]
	v_mfma_f32_16x16x32_bf16 v[38:41], v[148:151], v[200:203], v[38:41]
	v_mfma_f32_16x16x32_bf16 v[34:37], v[156:159], v[200:203], v[34:37]
	s_setprio 0
	s_barrier
	s_add_i32 s61, s61, 0x80180
	s_mov_b32 m0, s35
	s_nop 0
	buffer_load_dwordx4 v134, s[52:55], s61 offen lds
	s_mov_b32 m0, s36
	s_nop 0
	buffer_load_dwordx4 v135, s[52:55], s61 offen lds
	s_waitcnt vmcnt(6)
	s_barrier
	s_setprio 1
	v_mfma_f32_16x16x32_bf16 v[30:33], v[204:207], v[160:163], v[30:33]
	v_mfma_f32_16x16x32_bf16 v[26:29], v[214:217], v[160:163], v[26:29]
	v_mfma_f32_16x16x32_bf16 v[22:25], v[204:207], v[168:171], v[22:25]
	v_mfma_f32_16x16x32_bf16 v[18:21], v[214:217], v[168:171], v[18:21]
	v_mfma_f32_16x16x32_bf16 v[12:15], v[204:207], v[176:179], v[12:15]
	v_mfma_f32_16x16x32_bf16 v[8:11], v[214:217], v[176:179], v[8:11]
	v_mfma_f32_16x16x32_bf16 v[4:7], v[204:207], v[196:199], v[4:7]
	v_mfma_f32_16x16x32_bf16 v[0:3], v[214:217], v[196:199], v[0:3]
	v_mfma_f32_16x16x32_bf16 v[30:33], v[208:211], v[164:167], v[30:33]
	v_mfma_f32_16x16x32_bf16 v[26:29], v[218:221], v[164:167], v[26:29]
	v_mfma_f32_16x16x32_bf16 v[22:25], v[208:211], v[172:175], v[22:25]
	v_mfma_f32_16x16x32_bf16 v[18:21], v[218:221], v[172:175], v[18:21]
	v_mfma_f32_16x16x32_bf16 v[12:15], v[208:211], v[180:183], v[12:15]
	v_mfma_f32_16x16x32_bf16 v[8:11], v[218:221], v[180:183], v[8:11]
	v_mfma_f32_16x16x32_bf16 v[4:7], v[208:211], v[200:203], v[4:7]
	v_mfma_f32_16x16x32_bf16 v[0:3], v[218:221], v[200:203], v[0:3]
	s_setprio 0
	s_add_i32 s37, s37, 2
	s_addk_i32 s38, 0x100
	s_cmp_lt_u32 s37, 28
	s_barrier
	s_cbranch_scc1 .LBB0_646
	v_mov_b32_e32 v144, v130
	s_or_b32 s19, s19, 0x80f80
	v_and_b32_e32 v147, 15, v144
	v_bfe_u32 v146, v144, 4, 2
	v_lshlrev_b32_e32 v150, 2, v144
	v_bfe_u32 v145, v144, 6, 2
	v_lshlrev_b32_e32 v174, 4, v146
	v_lshlrev_b32_e32 v148, 6, v147
	v_and_b32_e32 v175, 32, v150
	v_lshlrev_b32_e32 v149, 12, v145
	v_bitop3_b32 v190, v174, v175, v148 bitop3:0x36
	v_add3_u32 v148, s78, v190, v149
	ds_read_b128 v[150:153], v148
	ds_read_b128 v[154:157], v148 offset:1024
	ds_read_b128 v[158:161], v148 offset:2048
	ds_read_b128 v[162:165], v148 offset:3072
	v_ashrrev_i32_e32 v148, 2, v144
	v_lshlrev_b32_e32 v177, 6, v144
	v_and_b32_e32 v148, 0xffffffc0, v148
	v_and_b32_e32 v177, 0x3c0, v177
	v_lshlrev_b32_e32 v176, 7, v148
	v_bitop3_b32 v174, v177, v175, v174 bitop3:0x36
	s_waitcnt vmcnt(0)
	v_add3_u32 v250, 0, v190, v176
	v_add3_u32 v251, 0, v174, v176
	s_mov_b32 m0, s13
	ds_read_b128 v[166:169], v250
	ds_read_b128 v[170:173], v250 offset:1024
	ds_read_b128 v[174:177], v251 offset:2048
	ds_read_b128 v[178:181], v251 offset:3072
	ds_read_b128 v[182:185], v251 offset:4096
	ds_read_b128 v[196:199], v251 offset:5120
	ds_read_b128 v[200:203], v251 offset:6144
	ds_read_b128 v[204:207], v251 offset:7168
	buffer_load_dwordx4 v134, s[48:51], s19 offen lds
	s_mov_b32 m0, s12
	s_nop 0
	buffer_load_dwordx4 v135, s[48:51], s19 offen lds
	s_barrier
	s_waitcnt lgkmcnt(0)
	s_setprio 1
	s_waitcnt lgkmcnt(0)
	v_mfma_f32_16x16x32_bf16 v[126:129], v[150:153], v[166:169], v[126:129]
	v_mfma_f32_16x16x32_bf16 v[122:125], v[158:161], v[166:169], v[122:125]
	v_mfma_f32_16x16x32_bf16 v[118:121], v[150:153], v[174:177], v[118:121]
	v_mfma_f32_16x16x32_bf16 v[114:117], v[158:161], v[174:177], v[114:117]
	v_mfma_f32_16x16x32_bf16 v[102:105], v[150:153], v[200:203], v[102:105]
	v_mfma_f32_16x16x32_bf16 v[98:101], v[158:161], v[200:203], v[98:101]
	v_mfma_f32_16x16x32_bf16 v[126:129], v[154:157], v[170:173], v[126:129]
	v_mfma_f32_16x16x32_bf16 v[122:125], v[162:165], v[170:173], v[122:125]
	v_mfma_f32_16x16x32_bf16 v[118:121], v[154:157], v[178:181], v[118:121]
	v_mfma_f32_16x16x32_bf16 v[114:117], v[162:165], v[178:181], v[114:117]
	v_mfma_f32_16x16x32_bf16 v[110:113], v[150:153], v[182:185], v[110:113]
	v_mfma_f32_16x16x32_bf16 v[106:109], v[158:161], v[182:185], v[106:109]
	v_mfma_f32_16x16x32_bf16 v[102:105], v[154:157], v[204:207], v[102:105]
	v_mfma_f32_16x16x32_bf16 v[98:101], v[162:165], v[204:207], v[98:101]
	v_mfma_f32_16x16x32_bf16 v[208:211], v[154:157], v[196:199], v[110:113]
	v_mfma_f32_16x16x32_bf16 v[214:217], v[162:165], v[196:199], v[106:109]
	s_setprio 0
	v_add3_u32 v222, s77, v190, v149
	s_barrier
	s_nop 0
	ds_read_b128 v[106:109], v222
	ds_read_b128 v[110:113], v222 offset:1024
	ds_read_b128 v[218:221], v222 offset:2048
	ds_read_b128 v[222:225], v222 offset:3072
	s_barrier
	s_waitcnt lgkmcnt(0)
	s_setprio 1
	s_waitcnt lgkmcnt(0)
	v_mfma_f32_16x16x32_bf16 v[94:97], v[106:109], v[166:169], v[94:97]
	v_mfma_f32_16x16x32_bf16 v[82:85], v[218:221], v[174:177], v[82:85]
	v_mfma_f32_16x16x32_bf16 v[78:81], v[106:109], v[182:185], v[78:81]
	v_mfma_f32_16x16x32_bf16 v[74:77], v[218:221], v[182:185], v[74:77]
	v_mfma_f32_16x16x32_bf16 v[70:73], v[106:109], v[200:203], v[70:73]
	v_mfma_f32_16x16x32_bf16 v[66:69], v[218:221], v[200:203], v[66:69]
	v_mfma_f32_16x16x32_bf16 v[94:97], v[110:113], v[170:173], v[94:97]
	v_mfma_f32_16x16x32_bf16 v[90:93], v[218:221], v[166:169], v[90:93]
	v_mfma_f32_16x16x32_bf16 v[86:89], v[106:109], v[174:177], v[86:89]
	v_mfma_f32_16x16x32_bf16 v[82:85], v[222:225], v[178:181], v[82:85]
	v_mfma_f32_16x16x32_bf16 v[78:81], v[110:113], v[196:199], v[78:81]
	v_mfma_f32_16x16x32_bf16 v[74:77], v[222:225], v[196:199], v[74:77]
	v_mfma_f32_16x16x32_bf16 v[70:73], v[110:113], v[204:207], v[70:73]
	v_mfma_f32_16x16x32_bf16 v[66:69], v[222:225], v[204:207], v[66:69]
	v_mfma_f32_16x16x32_bf16 v[166:169], v[222:225], v[170:173], v[90:93]
	v_mfma_f32_16x16x32_bf16 v[170:173], v[110:113], v[178:181], v[86:89]
	s_setprio 0
	s_barrier
	s_nop 0
	ds_read_b128 v[86:89], v250 offset:16384
	ds_read_b128 v[90:93], v250 offset:17408
	ds_read_b128 v[174:177], v251 offset:18432
	ds_read_b128 v[178:181], v251 offset:19456
	ds_read_b128 v[182:185], v251 offset:20480
	ds_read_b128 v[196:199], v251 offset:21504
	ds_read_b128 v[200:203], v251 offset:22528
	ds_read_b128 v[204:207], v251 offset:23552
	s_waitcnt vmcnt(4)
	s_barrier
	s_waitcnt lgkmcnt(0)
	s_setprio 1
	s_waitcnt lgkmcnt(0)
	v_mfma_f32_16x16x32_bf16 v[54:57], v[150:153], v[174:177], v[54:57]
	v_mfma_f32_16x16x32_bf16 v[50:53], v[158:161], v[174:177], v[50:53]
	v_mfma_f32_16x16x32_bf16 v[62:65], v[150:153], v[86:89], v[62:65]
	v_mfma_f32_16x16x32_bf16 v[58:61], v[158:161], v[86:89], v[58:61]
	v_mfma_f32_16x16x32_bf16 v[54:57], v[154:157], v[178:181], v[54:57]
	v_mfma_f32_16x16x32_bf16 v[50:53], v[162:165], v[178:181], v[50:53]
	v_mfma_f32_16x16x32_bf16 v[46:49], v[150:153], v[182:185], v[46:49]
	v_mfma_f32_16x16x32_bf16 v[42:45], v[158:161], v[182:185], v[42:45]
	v_mfma_f32_16x16x32_bf16 v[38:41], v[150:153], v[200:203], v[38:41]
	v_mfma_f32_16x16x32_bf16 v[34:37], v[158:161], v[200:203], v[34:37]
	v_mfma_f32_16x16x32_bf16 v[226:229], v[154:157], v[90:93], v[62:65]
	v_mfma_f32_16x16x32_bf16 v[230:233], v[162:165], v[90:93], v[58:61]
	v_mfma_f32_16x16x32_bf16 v[234:237], v[154:157], v[196:199], v[46:49]
	v_mfma_f32_16x16x32_bf16 v[238:241], v[162:165], v[196:199], v[42:45]
	v_mfma_f32_16x16x32_bf16 v[150:153], v[154:157], v[204:207], v[38:41]
	v_mfma_f32_16x16x32_bf16 v[154:157], v[162:165], v[204:207], v[34:37]
	s_setprio 0
	s_setprio 1
	v_mfma_f32_16x16x32_bf16 v[30:33], v[106:109], v[86:89], v[30:33]
	v_mfma_f32_16x16x32_bf16 v[26:29], v[218:221], v[86:89], v[26:29]
	v_mfma_f32_16x16x32_bf16 v[12:15], v[106:109], v[182:185], v[12:15]
	v_mfma_f32_16x16x32_bf16 v[8:11], v[218:221], v[182:185], v[8:11]
	v_mfma_f32_16x16x32_bf16 v[30:33], v[110:113], v[90:93], v[30:33]
	v_mfma_f32_16x16x32_bf16 v[26:29], v[222:225], v[90:93], v[26:29]
	v_mfma_f32_16x16x32_bf16 v[22:25], v[106:109], v[174:177], v[22:25]
	v_mfma_f32_16x16x32_bf16 v[18:21], v[218:221], v[174:177], v[18:21]
	v_mfma_f32_16x16x32_bf16 v[12:15], v[110:113], v[196:199], v[12:15]
	v_mfma_f32_16x16x32_bf16 v[8:11], v[222:225], v[196:199], v[8:11]
	v_mfma_f32_16x16x32_bf16 v[4:7], v[106:109], v[200:203], v[4:7]
	v_mfma_f32_16x16x32_bf16 v[0:3], v[218:221], v[200:203], v[0:3]
	v_mfma_f32_16x16x32_bf16 v[158:161], v[110:113], v[178:181], v[22:25]
	v_mfma_f32_16x16x32_bf16 v[162:165], v[222:225], v[178:181], v[18:21]
	v_mfma_f32_16x16x32_bf16 v[174:177], v[110:113], v[204:207], v[4:7]
	v_mfma_f32_16x16x32_bf16 v[178:181], v[222:225], v[204:207], v[0:3]
	s_setprio 0
	v_add3_u32 v18, s2, v190, v149
	s_barrier
	s_nop 0
	ds_read_b128 v[0:3], v18
	ds_read_b128 v[4:7], v18 offset:1024
	ds_read_b128 v[182:185], v18 offset:2048
	ds_read_b128 v[196:199], v18 offset:3072
	ds_read_b128 v[18:21], v250 offset:32768
	ds_read_b128 v[22:25], v250 offset:33792
	ds_read_b128 v[42:45], v251 offset:34816
	ds_read_b128 v[46:49], v251 offset:35840
	ds_read_b128 v[200:203], v251 offset:36864
	ds_read_b128 v[204:207], v251 offset:37888
	ds_read_b128 v[218:221], v251 offset:38912
	ds_read_b128 v[222:225], v251 offset:39936
	s_waitcnt vmcnt(2)
	s_barrier
	s_waitcnt lgkmcnt(0)
	s_setprio 1
	s_waitcnt lgkmcnt(0)
	v_mfma_f32_16x16x32_bf16 v[34:37], v[0:3], v[18:21], v[126:129]
	v_mfma_f32_16x16x32_bf16 v[110:113], v[4:7], v[22:25], v[34:37]
	v_mfma_f32_16x16x32_bf16 v[34:37], v[182:185], v[18:21], v[122:125]
	v_mfma_f32_16x16x32_bf16 v[106:109], v[196:199], v[22:25], v[34:37]
	v_mfma_f32_16x16x32_bf16 v[34:37], v[0:3], v[42:45], v[118:121]
	v_mfma_f32_16x16x32_bf16 v[90:93], v[4:7], v[46:49], v[34:37]
	v_mfma_f32_16x16x32_bf16 v[34:37], v[182:185], v[42:45], v[114:117]
	v_mfma_f32_16x16x32_bf16 v[86:89], v[196:199], v[46:49], v[34:37]
	v_mfma_f32_16x16x32_bf16 v[34:37], v[0:3], v[200:203], v[208:211]
	v_mfma_f32_16x16x32_bf16 v[62:65], v[4:7], v[204:207], v[34:37]
	v_mfma_f32_16x16x32_bf16 v[34:37], v[182:185], v[200:203], v[214:217]
	v_mfma_f32_16x16x32_bf16 v[58:61], v[196:199], v[204:207], v[34:37]
	v_mfma_f32_16x16x32_bf16 v[34:37], v[0:3], v[218:221], v[102:105]
	v_mfma_f32_16x16x32_bf16 v[38:41], v[4:7], v[222:225], v[34:37]
	v_mfma_f32_16x16x32_bf16 v[34:37], v[182:185], v[218:221], v[98:101]
	v_mfma_f32_16x16x32_bf16 v[34:37], v[196:199], v[222:225], v[34:37]
	s_setprio 0
	s_nop 0
	v_add3_u32 v98, s91, v190, v149
	s_barrier
	ds_read_b128 v[208:211], v98
	ds_read_b128 v[214:217], v98 offset:1024
	ds_read_b128 v[242:245], v98 offset:2048
	ds_read_b128 v[246:249], v98 offset:3072
	s_waitcnt vmcnt(0)
	s_barrier
	s_waitcnt lgkmcnt(0)
	s_setprio 1
	s_waitcnt lgkmcnt(0)
	v_mfma_f32_16x16x32_bf16 v[94:97], v[208:211], v[18:21], v[94:97]
	v_mfma_f32_16x16x32_bf16 v[18:21], v[242:245], v[18:21], v[166:169]
	v_mfma_f32_16x16x32_bf16 v[122:125], v[246:249], v[22:25], v[18:21]
	v_mfma_f32_16x16x32_bf16 v[18:21], v[208:211], v[42:45], v[170:173]
	v_mfma_f32_16x16x32_bf16 v[118:121], v[214:217], v[46:49], v[18:21]
	v_mfma_f32_16x16x32_bf16 v[18:21], v[242:245], v[42:45], v[82:85]
	v_mfma_f32_16x16x32_bf16 v[114:117], v[246:249], v[46:49], v[18:21]
	v_mfma_f32_16x16x32_bf16 v[18:21], v[208:211], v[200:203], v[78:81]
	v_mfma_f32_16x16x32_bf16 v[102:105], v[214:217], v[204:207], v[18:21]
	v_mfma_f32_16x16x32_bf16 v[18:21], v[242:245], v[200:203], v[74:77]
	v_mfma_f32_16x16x32_bf16 v[126:129], v[214:217], v[22:25], v[94:97]
	v_mfma_f32_16x16x32_bf16 v[94:97], v[246:249], v[204:207], v[18:21]
	v_mfma_f32_16x16x32_bf16 v[18:21], v[208:211], v[218:221], v[70:73]
	v_mfma_f32_16x16x32_bf16 v[70:73], v[214:217], v[222:225], v[18:21]
	v_mfma_f32_16x16x32_bf16 v[18:21], v[242:245], v[218:221], v[66:69]
	v_mfma_f32_16x16x32_bf16 v[66:69], v[246:249], v[222:225], v[18:21]
	s_setprio 0
	s_barrier
	ds_read_b128 v[82:85], v250 offset:49152
	ds_read_b128 v[166:169], v250 offset:50176
	ds_read_b128 v[170:173], v251 offset:51200
	ds_read_b128 v[200:203], v251 offset:52224
	ds_read_b128 v[204:207], v251 offset:53248
	ds_read_b128 v[218:221], v251 offset:54272
	ds_read_b128 v[222:225], v251 offset:55296
	ds_read_b128 v[250:253], v251 offset:56320
	s_barrier
	s_waitcnt lgkmcnt(0)
	s_setprio 1
	s_waitcnt lgkmcnt(0)
	v_mfma_f32_16x16x32_bf16 v[18:21], v[0:3], v[82:85], v[226:229]
	v_mfma_f32_16x16x32_bf16 v[78:81], v[4:7], v[166:169], v[18:21]
	v_mfma_f32_16x16x32_bf16 v[18:21], v[182:185], v[82:85], v[230:233]
	v_mfma_f32_16x16x32_bf16 v[74:77], v[196:199], v[166:169], v[18:21]
	v_mfma_f32_16x16x32_bf16 v[18:21], v[0:3], v[170:173], v[54:57]
	v_mfma_f32_16x16x32_bf16 v[46:49], v[4:7], v[200:203], v[18:21]
	v_mfma_f32_16x16x32_bf16 v[18:21], v[182:185], v[170:173], v[50:53]
	v_mfma_f32_16x16x32_bf16 v[42:45], v[196:199], v[200:203], v[18:21]
	v_mfma_f32_16x16x32_bf16 v[18:21], v[0:3], v[204:207], v[234:237]
	v_mfma_f32_16x16x32_bf16 v[0:3], v[0:3], v[222:225], v[150:153]
	v_mfma_f32_16x16x32_bf16 v[22:25], v[4:7], v[218:221], v[18:21]
	v_mfma_f32_16x16x32_bf16 v[18:21], v[182:185], v[204:207], v[238:241]
	v_mfma_f32_16x16x32_bf16 v[4:7], v[4:7], v[250:253], v[0:3]
	v_mfma_f32_16x16x32_bf16 v[0:3], v[182:185], v[222:225], v[154:157]
	v_mfma_f32_16x16x32_bf16 v[18:21], v[196:199], v[218:221], v[18:21]
	v_mfma_f32_16x16x32_bf16 v[0:3], v[196:199], v[250:253], v[0:3]
	s_setprio 0
	s_setprio 1
	v_mfma_f32_16x16x32_bf16 v[26:29], v[242:245], v[82:85], v[26:29]
	v_mfma_f32_16x16x32_bf16 v[30:33], v[208:211], v[82:85], v[30:33]
	v_mfma_f32_16x16x32_bf16 v[82:85], v[246:249], v[166:169], v[26:29]
	v_mfma_f32_16x16x32_bf16 v[26:29], v[208:211], v[170:173], v[158:161]
	v_mfma_f32_16x16x32_bf16 v[54:57], v[214:217], v[200:203], v[26:29]
	v_mfma_f32_16x16x32_bf16 v[26:29], v[242:245], v[170:173], v[162:165]
	v_mfma_f32_16x16x32_bf16 v[8:11], v[242:245], v[204:207], v[8:11]
	v_mfma_f32_16x16x32_bf16 v[50:53], v[246:249], v[200:203], v[26:29]
	v_mfma_f32_16x16x32_bf16 v[12:15], v[208:211], v[204:207], v[12:15]
	v_mfma_f32_16x16x32_bf16 v[26:29], v[246:249], v[218:221], v[8:11]
	v_mfma_f32_16x16x32_bf16 v[8:11], v[208:211], v[222:225], v[174:177]
	v_mfma_f32_16x16x32_bf16 v[98:101], v[214:217], v[166:169], v[30:33]
	v_mfma_f32_16x16x32_bf16 v[30:33], v[214:217], v[218:221], v[12:15]
	v_mfma_f32_16x16x32_bf16 v[12:15], v[214:217], v[250:253], v[8:11]
	v_mfma_f32_16x16x32_bf16 v[8:11], v[242:245], v[222:225], v[178:181]
	v_mfma_f32_16x16x32_bf16 v[8:11], v[246:249], v[250:253], v[8:11]
	s_setprio 0
	s_movk_i32 s1, 0x100
	s_nop 0
	v_cmp_gt_u32_e32 vcc, s1, v144
	s_barrier
	s_and_saveexec_b64 s[12:13], vcc
	s_cbranch_execz .LBB0_649
	s_barrier

.LBB0_650:
	v_or_b32_e32 v38, s14, v1
	v_mad_u64_u32 v[34:35], s[14:15], v38, s43, v[0:1]
	ds_read_b128 v[4:7], v34
	ds_read_b128 v[8:11], v34 offset:1056
	v_ashrrev_i32_e32 v39, 31, v38
	v_or_b32_e32 v40, 2, v38
	v_or_b32_e32 v42, 4, v38
	v_or_b32_e32 v44, 6, v38
	v_or_b32_e32 v46, 8, v38
	v_or_b32_e32 v48, 10, v38
	v_or_b32_e32 v50, 12, v38
	v_or_b32_e32 v52, 14, v38
	v_lshlrev_b64 v[38:39], 12, v[38:39]
	ds_read_b128 v[12:15], v34 offset:2112
	ds_read_b128 v[18:21], v34 offset:3168
	v_lshl_add_u64 v[38:39], v[2:3], 0, v[38:39]
	v_ashrrev_i32_e32 v41, 31, v40
	s_waitcnt lgkmcnt(3)
	global_store_dwordx4 v[38:39], v[4:7], off nt
	v_ashrrev_i32_e32 v43, 31, v42
	ds_read_b128 v[22:25], v34 offset:4224
	ds_read_b128 v[26:29], v34 offset:5280
	v_lshlrev_b64 v[4:5], 12, v[40:41]
	v_lshl_add_u64 v[4:5], v[2:3], 0, v[4:5]
	s_waitcnt lgkmcnt(4)
	global_store_dwordx4 v[4:5], v[8:11], off nt
	v_lshlrev_b64 v[4:5], 12, v[42:43]
	v_lshl_add_u64 v[4:5], v[2:3], 0, v[4:5]
	v_ashrrev_i32_e32 v45, 31, v44
	s_waitcnt lgkmcnt(3)
	global_store_dwordx4 v[4:5], v[12:15], off nt
	v_lshlrev_b64 v[4:5], 12, v[44:45]
	v_lshl_add_u64 v[4:5], v[2:3], 0, v[4:5]
	v_ashrrev_i32_e32 v47, 31, v46
	s_waitcnt lgkmcnt(2)
	global_store_dwordx4 v[4:5], v[18:21], off nt
	v_lshlrev_b64 v[4:5], 12, v[46:47]
	ds_read_b128 v[30:33], v34 offset:6336
	v_lshl_add_u64 v[4:5], v[2:3], 0, v[4:5]
	v_ashrrev_i32_e32 v49, 31, v48
	s_waitcnt lgkmcnt(2)
	global_store_dwordx4 v[4:5], v[22:25], off nt
	v_lshlrev_b64 v[4:5], 12, v[48:49]
	ds_read_b128 v[34:37], v34 offset:7392
	v_lshl_add_u64 v[4:5], v[2:3], 0, v[4:5]
	v_ashrrev_i32_e32 v51, 31, v50
	s_waitcnt lgkmcnt(2)
	global_store_dwordx4 v[4:5], v[26:29], off nt
	v_lshlrev_b64 v[4:5], 12, v[50:51]
	v_lshl_add_u64 v[4:5], v[2:3], 0, v[4:5]
	v_ashrrev_i32_e32 v53, 31, v52
	s_waitcnt lgkmcnt(1)
	global_store_dwordx4 v[4:5], v[30:33], off nt
	v_lshlrev_b64 v[4:5], 12, v[52:53]
	v_lshl_add_u64 v[4:5], v[2:3], 0, v[4:5]
	s_mov_b32 s14, 16
	s_and_b64 vcc, exec, s[12:13]
	s_mov_b64 s[12:13], 0
	s_waitcnt lgkmcnt(0)
	global_store_dwordx4 v[4:5], v[34:37], off nt
	s_cbranch_vccnz .LBB0_650
	s_add_i32 s18, s18, 1
	s_mov_b64 s[14:15], 0
	s_barrier
	s_barrier
	s_branch .LBB0_637
	s_nop 0
